# fold the softmax reference into the QK accumulator init (C block = -m): fast path needs no per-element subtract; rescale path updates the C block
# speedup vs baseline: 1.0112x; 1.0064x over previous
; #define VRDK(L, H, KS) do { _Pragma("unroll") for (int d0 = 0; d0 < 4; ++d0) { L[d0] = vtr(vp + v_rd_off(d0, KS, 0)); H[d0] = vtr(vp + v_rd_off(d0, KS, 1)); } } while (0)
; #define PVK(pa, L, H) do { _Pragma("unroll") for (int d0 = 0; d0 < 4; ++d0) o[d0] = __builtin_amdgcn_mfma_f32_32x32x16_bf16(pa, PK(L[d0], H[d0]), o[d0], 0, 0, 0); } while (0)
; __device__ __forceinline__ void finishSM(f32x16& p0, f32x16& p1, float alpha, float& l_reg, bf16x8& pa0, bf16x8& pa1, bf16x8& pa2, bf16x8& pa3) {
; #pragma unroll
;   for (int r = 0; r < 16; ++r) p1[r] = __builtin_amdgcn_exp2f(p1[r]);
;   float ps = 0;
; #pragma unroll
;   for (int r = 0; r < 16; ++r) ps += p0[r];
; #pragma unroll
;   for (int r = 0; r < 16; ++r) ps += p1[r];
;   { auto rr = __builtin_amdgcn_permlane32_swap(__float_as_uint(ps), __float_as_uint(ps), false, false);
;     ps = __uint_as_float(rr[0]) + __uint_as_float(rr[1]); }
;   l_reg = l_reg * alpha + ps;
;     ...
;   PK4(p0, 0, pa0); PK4(p0, 8, pa1); PK4(p1, 0, pa2); PK4(p1, 8, pa3);
;     ...
; }
; template <bool PIPE> __device__ __forceinline__ void pv_d0(f32x16* o, lds_cptr vp, bf16x8 pa0, bf16x8 pa1, bf16x8 pa2, bf16x8 pa3) {
;   s16x4 La[4], Ha[4], Lb[4], Hb[4];
;   if constexpr (!PIPE) {
;     VRDK(La, Ha, 0); PVK(pa0, La, Ha); VRDK(La, Ha, 1); PVK(pa1, La, Ha); VRDK(La, Ha, 2); PVK(pa2, La, Ha); VRDK(La, Ha, 3); PVK(pa3, La, Ha);
;     return;
;   }
;   VRDK(La, Ha, 0); VRDK(Lb, Hb, 1);
;   PVK(pa0, La, Ha); VRDK(La, Ha, 2);
;   PVK(pa1, Lb, Hb); VRDK(Lb, Hb, 3);
;   PVK(pa2, La, Ha); PVK(pa3, Lb, Hb);
;   __builtin_amdgcn_sched_group_barrier(0x100, 16, 0); __builtin_amdgcn_sched_group_barrier(0x008, 4, 0);
;   __builtin_amdgcn_sched_group_barrier(0x100, 8, 0);  __builtin_amdgcn_sched_group_barrier(0x008, 4, 0);
;   __builtin_amdgcn_sched_group_barrier(0x100, 8, 0);  __builtin_amdgcn_sched_group_barrier(0x008, 8, 0);
; }
.LBB0_331:
	v_cndmask_b32_e64 v223, v49, v206, s[40:41]
	v_sub_f32_e32 v188, 0, v223
	v_sub_f32_e32 v116, 0, v223
	v_sub_f32_e32 v117, 0, v223
	v_sub_f32_e32 v118, 0, v223
	v_sub_f32_e32 v119, 0, v223
	v_sub_f32_e32 v120, 0, v223
	v_sub_f32_e32 v121, 0, v223
	v_sub_f32_e32 v122, 0, v223
	v_sub_f32_e32 v123, 0, v223
	v_sub_f32_e32 v124, 0, v223
	v_sub_f32_e32 v125, 0, v223
	v_sub_f32_e32 v126, 0, v223
	v_sub_f32_e32 v127, 0, v223
	v_sub_f32_e32 v128, 0, v223
	v_sub_f32_e32 v129, 0, v223
	v_sub_f32_e32 v130, 0, v223
	v_sub_f32_e32 v131, 0, v223
	v_sub_f32_e32 v16, v16, v223
	v_sub_f32_e32 v17, v17, v223
	v_exp_f32_e32 v16, v16
	v_sub_f32_e32 v18, v18, v223
	v_exp_f32_e32 v17, v17
	v_sub_f32_e32 v19, v19, v223
	v_exp_f32_e32 v18, v18
	v_sub_f32_e32 v20, v20, v223
	v_exp_f32_e32 v19, v19
	v_sub_f32_e32 v21, v21, v223
	v_exp_f32_e32 v20, v20
	v_add_f32_e32 v49, 0, v16
	v_sub_f32_e32 v22, v22, v223
	v_exp_f32_e32 v21, v21
	v_add_f32_e32 v49, v17, v49
	v_sub_f32_e32 v23, v23, v223
	v_exp_f32_e32 v22, v22
	v_add_f32_e32 v49, v18, v49
	v_sub_f32_e32 v24, v24, v223
	v_exp_f32_e32 v23, v23
	v_add_f32_e32 v49, v19, v49
	v_sub_f32_e32 v25, v25, v223
	v_exp_f32_e32 v24, v24
	v_add_f32_e32 v49, v20, v49
	v_sub_f32_e32 v26, v26, v223
	v_exp_f32_e32 v25, v25
	v_add_f32_e32 v49, v21, v49
	v_sub_f32_e32 v27, v27, v223
	v_exp_f32_e32 v26, v26
	v_add_f32_e32 v49, v22, v49
	v_sub_f32_e32 v28, v28, v223
	v_exp_f32_e32 v27, v27
	v_add_f32_e32 v49, v23, v49
	v_sub_f32_e32 v29, v29, v223
	v_exp_f32_e32 v28, v28
	v_add_f32_e32 v49, v24, v49
	v_sub_f32_e32 v30, v30, v223
	v_exp_f32_e32 v29, v29
	v_add_f32_e32 v49, v25, v49
	v_sub_f32_e32 v31, v31, v223
	v_exp_f32_e32 v30, v30
	v_add_f32_e32 v49, v26, v49
	v_sub_f32_e32 v32, v32, v223
	v_exp_f32_e32 v31, v31
	v_add_f32_e32 v49, v27, v49
	v_sub_f32_e32 v33, v33, v223
	v_exp_f32_e32 v32, v32
	v_add_f32_e32 v49, v28, v49
	v_sub_f32_e32 v34, v34, v223
	v_exp_f32_e32 v33, v33
	v_add_f32_e32 v49, v29, v49
	v_sub_f32_e32 v35, v35, v223
	v_exp_f32_e32 v34, v34
	v_add_f32_e32 v49, v30, v49
	v_sub_f32_e32 v36, v36, v223
	v_exp_f32_e32 v35, v35
	v_add_f32_e32 v49, v31, v49
	v_sub_f32_e32 v37, v37, v223
	v_exp_f32_e32 v36, v36
	v_add_f32_e32 v49, v32, v49
	v_sub_f32_e32 v38, v38, v223
	v_exp_f32_e32 v37, v37
	v_add_f32_e32 v49, v33, v49
	v_sub_f32_e32 v39, v39, v223
	v_exp_f32_e32 v38, v38
	v_add_f32_e32 v49, v34, v49
	v_sub_f32_e32 v40, v40, v223
	v_exp_f32_e32 v39, v39
	v_add_f32_e32 v49, v35, v49
	v_sub_f32_e32 v41, v41, v223
	v_exp_f32_e32 v40, v40
	v_add_f32_e32 v49, v36, v49
	v_sub_f32_e32 v42, v42, v223
	v_exp_f32_e32 v41, v41
	v_add_f32_e32 v49, v37, v49
	v_sub_f32_e32 v43, v43, v223
	v_exp_f32_e32 v42, v42
	v_add_f32_e32 v49, v38, v49
	v_sub_f32_e32 v44, v44, v223
	v_exp_f32_e32 v43, v43
	v_add_f32_e32 v49, v39, v49
	v_sub_f32_e32 v45, v45, v223
	v_exp_f32_e32 v44, v44
	v_add_f32_e32 v49, v40, v49
	v_sub_f32_e32 v46, v46, v223
	v_exp_f32_e32 v45, v45
	v_add_f32_e32 v49, v41, v49
	v_sub_f32_e32 v47, v47, v223
	v_exp_f32_e32 v46, v46
	v_add_f32_e32 v49, v42, v49
	v_exp_f32_e32 v47, v47
	v_add_f32_e32 v49, v43, v49
	v_add_f32_e32 v49, v44, v49
	v_add_f32_e32 v49, v45, v49
	v_add_f32_e32 v49, v46, v49
	v_add_f32_e32 v49, v47, v49
	v_mov_b32_e32 v50, v49
	s_nop 1
	v_permlane32_swap_b32_e32 v49, v50
	v_add_f32_e32 v222, v49, v50
	v_cvt_pk_bf16_f32 v68, v16, v17
	v_cvt_pk_bf16_f32 v69, v18, v19
	v_cvt_pk_bf16_f32 v70, v20, v21
	v_cvt_pk_bf16_f32 v71, v22, v23
	v_cvt_pk_bf16_f32 v72, v24, v25
	v_cvt_pk_bf16_f32 v73, v26, v27
	v_cvt_pk_bf16_f32 v74, v28, v29
	v_cvt_pk_bf16_f32 v75, v30, v31
	v_cvt_pk_bf16_f32 v76, v32, v33
	v_cvt_pk_bf16_f32 v77, v34, v35
	v_cvt_pk_bf16_f32 v78, v36, v37
	v_cvt_pk_bf16_f32 v79, v38, v39
	v_cvt_pk_bf16_f32 v80, v40, v41
	v_cvt_pk_bf16_f32 v81, v42, v43
	v_cvt_pk_bf16_f32 v82, v44, v45
	v_cvt_pk_bf16_f32 v83, v46, v47
	v_fmac_f32_e32 v222, 0, v48
	v_or_b32_e32 v195, 0x2000, v216
	s_add_i32 s0, 0, 0x14000
	v_add_u32_e32 v16, s0, v212
	v_add_u32_e32 v17, s0, v211
	s_add_u32 s0, s34, 0x481800
	s_addc_u32 s1, s35, 0
	s_waitcnt vmcnt(7)
	ds_write_b128 v64, v[132:135] offset:32768
	s_waitcnt vmcnt(6)
	ds_write_b128 v65, v[136:139] offset:32768
	s_waitcnt vmcnt(5)
	ds_write_b128 v17, v[140:143]
	s_waitcnt vmcnt(4)
	ds_write_b128 v16, v[144:147]
	s_add_u32 s10, s34, 0x481000
	v_lshl_add_u64 v[16:17], s[0:1], 0, v[184:185]
	s_addc_u32 s11, s35, 0
	global_load_dwordx4 v[164:167], v[16:17], off
	v_lshl_add_u64 v[16:17], s[0:1], 0, v[186:187]
	global_load_dwordx4 v[168:171], v[16:17], off
	v_lshl_add_u64 v[16:17], s[10:11], 0, v[184:185]
	global_load_dwordx4 v[172:175], v[16:17], off
	v_lshl_add_u64 v[16:17], s[10:11], 0, v[186:187]
	global_load_dwordx4 v[176:179], v[16:17], off
	s_mov_b32 s12, 1
	s_setprio 1
	ds_read_b64_tr_b16 v[16:17], v214
	ds_read_b64_tr_b16 v[18:19], v214 offset:2048
	ds_read_b64_tr_b16 v[20:21], v214 offset:512
	ds_read_b64_tr_b16 v[22:23], v214 offset:2560
	ds_read_b64_tr_b16 v[84:85], v214 offset:1024
	ds_read_b64_tr_b16 v[86:87], v214 offset:3072
	ds_read_b64_tr_b16 v[88:89], v214 offset:1536
	ds_read_b64_tr_b16 v[90:91], v214 offset:3584
	ds_read_b64_tr_b16 v[92:93], v214 offset:4096
	ds_read_b64_tr_b16 v[94:95], v214 offset:6144
	ds_read_b64_tr_b16 v[224:225], v214 offset:4608
	ds_read_b64_tr_b16 v[226:227], v214 offset:6656
	ds_read_b64_tr_b16 v[228:229], v214 offset:5120
	ds_read_b64_tr_b16 v[230:231], v214 offset:7168
	ds_read_b64_tr_b16 v[232:233], v214 offset:5632
	ds_read_b64_tr_b16 v[234:235], v214 offset:7680
	s_waitcnt lgkmcnt(14)
	v_mfma_f32_32x32x16_bf16 v[32:47], v[68:71], v[16:19], v[0:15]
	s_waitcnt lgkmcnt(12)
	v_mfma_f32_32x32x16_bf16 v[48:63], v[68:71], v[20:23], v[0:15]
	s_waitcnt lgkmcnt(10)
; __device__ __forceinline__ void partialSM(f32x16& p0, f32x16& p1, float& m_reg, float& alpha) {
;   constexpr float THR2 = THR * 1.4426950408889634f;
;   float pmax = p0[0];
; #pragma unroll
;   for (int r = 1; r < 16; ++r) pmax = fmaxf(pmax, p0[r]);
; #pragma unroll
;   for (int r = 0; r < 16; ++r) pmax = fmaxf(pmax, p1[r]);
;   { auto rr = __builtin_amdgcn_permlane32_swap(__float_as_uint(pmax), __float_as_uint(pmax), false, false);
;     pmax = fmaxf(__uint_as_float(rr[0]), __uint_as_float(rr[1])); }
;   float mn;
;   if (__builtin_expect(__all(pmax - m_reg <= THR2), 1)) { mn = m_reg; alpha = 1.f; }
;   else { mn = fmaxf(m_reg, pmax); alpha = __builtin_amdgcn_exp2f(m_reg - mn); m_reg = mn; }
; #pragma unroll
;   for (int r = 0; r < 16; ++r) { p0[r] -= mn; p1[r] -= mn; }
; #pragma unroll
;   for (int r = 0; r < 16; ++r) p0[r] = __builtin_amdgcn_exp2f(p0[r]);
; }
; template <int NQ, bool QREG> __device__ __forceinline__ void qkt(f32x16& p0, f32x16& p1, const bf16_t* Ks, const bf16x8* qr, const bf16_t* Qw, int r32, int hi, int qcolB) {
;   p0 = f32x16{}; p1 = f32x16{};
; #pragma unroll
;   for (int d0 = 0; d0 < NQ; ++d0) { int cb = qcolB + (d0 * 16 + hi * 8) * 2;
;     bf16x8 b0 = *reinterpret_cast<const bf16x8*>((const char*)Ks + KSWZ(r32, cb));
;     bf16x8 b1 = *reinterpret_cast<const bf16x8*>((const char*)Ks + KSWZ(32 + r32, cb));
;     const bf16x8 qv = QREG ? qr[d0] : ld8(Qw + d0 * 16);
;     p0 = __builtin_amdgcn_mfma_f32_32x32x16_bf16(b0, qv, p0, 0, 0, 0); p1 = __builtin_amdgcn_mfma_f32_32x32x16_bf16(b1, qv, p1, 0, 0, 0); }
;   if (QREG) { __builtin_amdgcn_sched_group_barrier(0x100, 2 * NQ, 0); __builtin_amdgcn_sched_group_barrier(0x008, 2 * NQ, 0); }
; }
	v_mfma_f32_32x32x16_bf16 v[16:31], v[68:71], v[84:87], v[0:15]
	s_waitcnt lgkmcnt(8)
	v_mfma_f32_32x32x16_bf16 v[0:15], v[68:71], v[88:91], v[0:15]
	ds_read_b64_tr_b16 v[68:69], v214 offset:8192
	ds_read_b64_tr_b16 v[70:71], v214 offset:10240
	ds_read_b64_tr_b16 v[84:85], v214 offset:8704
	ds_read_b64_tr_b16 v[86:87], v214 offset:10752
	ds_read_b64_tr_b16 v[88:89], v214 offset:9216
	ds_read_b64_tr_b16 v[90:91], v214 offset:11264
	ds_read_b64_tr_b16 v[236:237], v214 offset:9728
	ds_read_b64_tr_b16 v[238:239], v214 offset:11776
	s_waitcnt lgkmcnt(14)
	v_mfma_f32_32x32x16_bf16 v[32:47], v[72:75], v[92:95], v[32:47]
	s_waitcnt lgkmcnt(12)
	v_mfma_f32_32x32x16_bf16 v[48:63], v[72:75], v[224:227], v[48:63]
	s_waitcnt lgkmcnt(10)
	v_mfma_f32_32x32x16_bf16 v[16:31], v[72:75], v[228:231], v[16:31]
	s_waitcnt lgkmcnt(8)
	v_mfma_f32_32x32x16_bf16 v[0:15], v[72:75], v[232:235], v[0:15]
	ds_read_b64_tr_b16 v[72:73], v214 offset:12288
	ds_read_b64_tr_b16 v[74:75], v214 offset:14336
	ds_read_b64_tr_b16 v[92:93], v214 offset:12800
	ds_read_b64_tr_b16 v[94:95], v214 offset:14848
	ds_read_b64_tr_b16 v[224:225], v214 offset:13312
	ds_read_b64_tr_b16 v[226:227], v214 offset:15360
	ds_read_b64_tr_b16 v[228:229], v214 offset:13824
	ds_read_b64_tr_b16 v[230:231], v214 offset:15872
	s_waitcnt lgkmcnt(14)
	v_mfma_f32_32x32x16_bf16 v[32:47], v[76:79], v[68:71], v[32:47]
	s_waitcnt lgkmcnt(12)
	v_mfma_f32_32x32x16_bf16 v[48:63], v[76:79], v[84:87], v[48:63]
	s_waitcnt lgkmcnt(10)
	v_mfma_f32_32x32x16_bf16 v[16:31], v[76:79], v[88:91], v[16:31]
	s_waitcnt lgkmcnt(8)
	v_mfma_f32_32x32x16_bf16 v[0:15], v[76:79], v[236:239], v[0:15]
	s_waitcnt lgkmcnt(6)
	v_mfma_f32_32x32x16_bf16 v[32:47], v[80:83], v[72:75], v[32:47]
	s_waitcnt lgkmcnt(4)
	v_mfma_f32_32x32x16_bf16 v[48:63], v[80:83], v[92:95], v[48:63]
	s_waitcnt lgkmcnt(2)
	v_mfma_f32_32x32x16_bf16 v[16:31], v[80:83], v[224:227], v[16:31]
	s_waitcnt lgkmcnt(0)
	v_mfma_f32_32x32x16_bf16 v[0:15], v[80:83], v[228:231], v[0:15]
	v_add_u32_e32 v64, s8, v218
	ds_read_b128 v[68:71], v64
	v_add3_u32 v64, v66, v195, s8
	ds_read_b128 v[80:83], v64
	v_add3_u32 v194, v194, v195, s8
	v_add_u32_e32 v224, s8, v219
	ds_read_b128 v[228:231], v194
	ds_read_b128 v[224:227], v224
	v_add3_u32 v193, v193, v195, s8
	v_add_u32_e32 v194, s8, v220
	v_add3_u32 v192, v192, v195, s8
	s_waitcnt lgkmcnt(2)
	v_mfma_f32_32x32x16_bf16 v[80:95], v[80:83], v[104:107], v[116:131]
	s_waitcnt lgkmcnt(1)
	v_mfma_f32_32x32x16_bf16 v[80:95], v[228:231], v[108:111], v[80:95]
	ds_read_b128 v[228:231], v193
	v_add_u32_e32 v193, s8, v221
	v_mfma_f32_32x32x16_bf16 v[64:79], v[68:71], v[104:107], v[116:131]
	s_waitcnt lgkmcnt(1)
	v_mfma_f32_32x32x16_bf16 v[64:79], v[224:227], v[108:111], v[64:79]
	ds_read_b128 v[224:227], v194
	s_waitcnt lgkmcnt(0)
	v_mfma_f32_32x32x16_bf16 v[64:79], v[224:227], v[112:115], v[64:79]
	ds_read_b128 v[224:227], v193
	ds_read_b128 v[192:195], v192
	v_mfma_f32_32x32x16_bf16 v[80:95], v[228:231], v[112:115], v[80:95]
	s_waitcnt lgkmcnt(1)
	v_mfma_f32_32x32x16_bf16 v[64:79], v[224:227], v[100:103], v[64:79]
	s_waitcnt lgkmcnt(0)
	v_mfma_f32_32x32x16_bf16 v[80:95], v[192:195], v[100:103], v[80:95]
	s_setprio 0
	s_lshl_b32 s0, s7, 1
	s_and_b32 s0, s0, 0x700
	s_add_u32 s0, s6, s0
	s_waitcnt lgkmcnt(0)
	s_barrier
	s_addc_u32 s1, s5, 0
	v_readlane_b32 s8, v251, 11
	v_readlane_b32 s9, v251, 12
	s_add_u32 s0, s8, s0
	s_addc_u32 s1, s9, s1
	s_mov_b32 s10, 0
	s_mov_b32 s9, 2
	s_mov_b32 s8, 6
.LBB0_332:
	s_mov_b32 s11, s9
	s_mov_b32 s9, s12
	v_max3_f32 v192, v64, v65, v66
	v_max3_f32 v192, v192, v67, v68
	v_max3_f32 v192, v192, v69, v70
	v_max3_f32 v192, v192, v71, v72
	v_max3_f32 v192, v192, v73, v74
	v_max3_f32 v192, v192, v75, v76
	v_max3_f32 v192, v192, v77, v78
	v_max3_f32 v192, v192, v79, v80
	v_max3_f32 v192, v192, v81, v82
	v_max3_f32 v192, v192, v83, v84
	v_max3_f32 v192, v192, v85, v86
	v_max3_f32 v192, v192, v87, v88
	v_max3_f32 v192, v192, v89, v90
	v_max3_f32 v192, v192, v91, v92
	v_max3_f32 v192, v192, v93, v94
	v_max_f32_e32 v192, v192, v95
	v_mov_b32_e32 v193, v192
	s_nop 1
	v_permlane32_swap_b32_e32 v192, v193
	v_max_f32_e32 v192, v192, v193
	v_cmp_ge_f32_e32 vcc, s19, v192
	s_cmp_eq_u64 vcc, exec
	s_cbranch_scc0 .Lw2slow_g1a
	v_exp_f32_e32 v64, v64
	v_exp_f32_e32 v65, v65
	v_exp_f32_e32 v66, v66
	v_add_f32_e32 v225, v65, v64
	v_exp_f32_e32 v67, v67
	v_add_f32_e32 v225, v66, v225
	v_exp_f32_e32 v68, v68
	v_add_f32_e32 v225, v67, v225
	v_exp_f32_e32 v69, v69
	v_add_f32_e32 v225, v68, v225
	v_exp_f32_e32 v70, v70
	v_add_f32_e32 v225, v69, v225
	v_exp_f32_e32 v71, v71
	v_add_f32_e32 v225, v70, v225
	v_exp_f32_e32 v72, v72
	v_add_f32_e32 v225, v71, v225
	v_exp_f32_e32 v73, v73
	v_add_f32_e32 v225, v72, v225
	v_exp_f32_e32 v74, v74
	v_add_f32_e32 v225, v73, v225
	v_exp_f32_e32 v75, v75
	v_add_f32_e32 v225, v74, v225
	v_exp_f32_e32 v192, v76
	v_add_f32_e32 v225, v75, v225
	v_exp_f32_e32 v193, v77
	v_add_f32_e32 v225, v192, v225
	v_exp_f32_e32 v194, v78
	v_add_f32_e32 v225, v193, v225
	v_exp_f32_e32 v195, v79
	v_add_f32_e32 v225, v194, v225
	v_exp_f32_e32 v80, v80
	v_add_f32_e32 v225, v195, v225
	v_exp_f32_e32 v81, v81
	v_add_f32_e32 v225, v80, v225
	v_exp_f32_e32 v82, v82
	v_add_f32_e32 v225, v81, v225
	v_exp_f32_e32 v83, v83
	v_add_f32_e32 v225, v82, v225
	v_exp_f32_e32 v84, v84
	v_add_f32_e32 v225, v83, v225
	v_exp_f32_e32 v85, v85
	v_add_f32_e32 v225, v84, v225
	v_exp_f32_e32 v86, v86
	v_add_f32_e32 v225, v85, v225
	v_exp_f32_e32 v87, v87
	v_add_f32_e32 v225, v86, v225
	v_exp_f32_e32 v88, v88
	v_add_f32_e32 v225, v87, v225
	v_exp_f32_e32 v89, v89
	v_add_f32_e32 v225, v88, v225
	v_exp_f32_e32 v90, v90
	v_add_f32_e32 v225, v89, v225
	v_exp_f32_e32 v91, v91
	v_add_f32_e32 v225, v90, v225
	v_exp_f32_e32 v92, v92
	v_add_f32_e32 v225, v91, v225
	v_exp_f32_e32 v93, v93
	v_add_f32_e32 v225, v92, v225
	v_exp_f32_e32 v94, v94
	v_add_f32_e32 v225, v93, v225
	v_exp_f32_e32 v95, v95
	v_add_f32_e32 v225, v94, v225
	v_cvt_pk_bf16_f32 v76, v64, v65
	v_add_f32_e32 v225, v95, v225
	v_mov_b32_e32 v226, v225
	v_cvt_pk_bf16_f32 v77, v66, v67
	v_cvt_pk_bf16_f32 v78, v68, v69
	v_cvt_pk_bf16_f32 v79, v70, v71
	v_cvt_pk_bf16_f32 v72, v72, v73
	v_cvt_pk_bf16_f32 v73, v74, v75
	v_cvt_pk_bf16_f32 v74, v192, v193
	v_cvt_pk_bf16_f32 v75, v194, v195
	v_cvt_pk_bf16_f32 v68, v80, v81
	v_cvt_pk_bf16_f32 v69, v82, v83
	v_cvt_pk_bf16_f32 v70, v84, v85
	v_cvt_pk_bf16_f32 v71, v86, v87
	v_cvt_pk_bf16_f32 v64, v88, v89
	v_cvt_pk_bf16_f32 v65, v90, v91
	v_cvt_pk_bf16_f32 v66, v92, v93
	v_cvt_pk_bf16_f32 v67, v94, v95
	v_permlane32_swap_b32_e32 v225, v226
	v_add_f32_e32 v222, v222, v225
	v_add_f32_e32 v222, v222, v226

; #define VRDK(L, H, KS) do { _Pragma("unroll") for (int d0 = 0; d0 < 4; ++d0) { L[d0] = vtr(vp + v_rd_off(d0, KS, 0)); H[d0] = vtr(vp + v_rd_off(d0, KS, 1)); } } while (0)
; #define PVK(pa, L, H) do { _Pragma("unroll") for (int d0 = 0; d0 < 4; ++d0) o[d0] = __builtin_amdgcn_mfma_f32_32x32x16_bf16(pa, PK(L[d0], H[d0]), o[d0], 0, 0, 0); } while (0)
; template <int NQ, bool QREG> __device__ __forceinline__ void qkt(f32x16& p0, f32x16& p1, const bf16_t* Ks, const bf16x8* qr, const bf16_t* Qw, int r32, int hi, int qcolB) {
;   p0 = f32x16{}; p1 = f32x16{};
; #pragma unroll
;   for (int d0 = 0; d0 < NQ; ++d0) { int cb = qcolB + (d0 * 16 + hi * 8) * 2;
;     bf16x8 b0 = *reinterpret_cast<const bf16x8*>((const char*)Ks + KSWZ(r32, cb));
;     bf16x8 b1 = *reinterpret_cast<const bf16x8*>((const char*)Ks + KSWZ(32 + r32, cb));
;     const bf16x8 qv = QREG ? qr[d0] : ld8(Qw + d0 * 16);
;     p0 = __builtin_amdgcn_mfma_f32_32x32x16_bf16(b0, qv, p0, 0, 0, 0); p1 = __builtin_amdgcn_mfma_f32_32x32x16_bf16(b1, qv, p1, 0, 0, 0); }
;   if (QREG) { __builtin_amdgcn_sched_group_barrier(0x100, 2 * NQ, 0); __builtin_amdgcn_sched_group_barrier(0x008, 2 * NQ, 0); }
; }
; template <bool PIPE> __device__ __forceinline__ void pv_d0(f32x16* o, lds_cptr vp, bf16x8 pa0, bf16x8 pa1, bf16x8 pa2, bf16x8 pa3) {
;   s16x4 La[4], Ha[4], Lb[4], Hb[4];
;   if constexpr (!PIPE) {
;     VRDK(La, Ha, 0); PVK(pa0, La, Ha); VRDK(La, Ha, 1); PVK(pa1, La, Ha); VRDK(La, Ha, 2); PVK(pa2, La, Ha); VRDK(La, Ha, 3); PVK(pa3, La, Ha);
;     return;
;   }
;   VRDK(La, Ha, 0); VRDK(Lb, Hb, 1);
;   PVK(pa0, La, Ha); VRDK(La, Ha, 2);
;   PVK(pa1, Lb, Hb); VRDK(Lb, Hb, 3);
;   PVK(pa2, La, Ha); PVK(pa3, Lb, Hb);
;   __builtin_amdgcn_sched_group_barrier(0x100, 16, 0); __builtin_amdgcn_sched_group_barrier(0x008, 4, 0);
;   __builtin_amdgcn_sched_group_barrier(0x100, 8, 0);  __builtin_amdgcn_sched_group_barrier(0x008, 4, 0);
;   __builtin_amdgcn_sched_group_barrier(0x100, 8, 0);  __builtin_amdgcn_sched_group_barrier(0x008, 8, 0);
; }
.LBB0_340:
	s_lshl_b32 s12, s11, 14
	s_lshl_b32 s13, s9, 14
	s_add_i32 s14, s12, 0
	s_setprio 1
	v_add_u32_e32 v227, s13, v214
	ds_read_b64_tr_b16 v[80:81], v227
	ds_read_b64_tr_b16 v[82:83], v227 offset:2048
	ds_read_b64_tr_b16 v[84:85], v227 offset:512
	ds_read_b64_tr_b16 v[86:87], v227 offset:2560
	ds_read_b64_tr_b16 v[88:89], v227 offset:1024
	ds_read_b64_tr_b16 v[90:91], v227 offset:3072
	ds_read_b64_tr_b16 v[92:93], v227 offset:1536
	ds_read_b64_tr_b16 v[94:95], v227 offset:3584
	ds_read_b64_tr_b16 v[228:229], v227 offset:4096
	ds_read_b64_tr_b16 v[230:231], v227 offset:6144
	ds_read_b64_tr_b16 v[232:233], v227 offset:4608
	ds_read_b64_tr_b16 v[234:235], v227 offset:6656
	ds_read_b64_tr_b16 v[236:237], v227 offset:5120
	ds_read_b64_tr_b16 v[238:239], v227 offset:7168
	ds_read_b64_tr_b16 v[240:241], v227 offset:5632
	ds_read_b64_tr_b16 v[242:243], v227 offset:7680
	s_waitcnt lgkmcnt(14)
	v_mfma_f32_32x32x16_bf16 v[32:47], v[76:79], v[80:83], v[32:47]
	s_waitcnt lgkmcnt(12)
	v_mfma_f32_32x32x16_bf16 v[48:63], v[76:79], v[84:87], v[48:63]
	s_waitcnt lgkmcnt(10)
	v_mfma_f32_32x32x16_bf16 v[16:31], v[76:79], v[88:91], v[16:31]
	s_waitcnt lgkmcnt(8)
	v_mfma_f32_32x32x16_bf16 v[0:15], v[76:79], v[92:95], v[0:15]
	ds_read_b64_tr_b16 v[76:77], v227 offset:8192
	ds_read_b64_tr_b16 v[78:79], v227 offset:10240
	ds_read_b64_tr_b16 v[80:81], v227 offset:8704
	ds_read_b64_tr_b16 v[82:83], v227 offset:10752
	ds_read_b64_tr_b16 v[84:85], v227 offset:9216
	ds_read_b64_tr_b16 v[86:87], v227 offset:11264
	ds_read_b64_tr_b16 v[88:89], v227 offset:9728
	ds_read_b64_tr_b16 v[90:91], v227 offset:11776
	s_waitcnt lgkmcnt(14)
	v_mfma_f32_32x32x16_bf16 v[32:47], v[72:75], v[228:231], v[32:47]
	s_waitcnt lgkmcnt(12)
	v_mfma_f32_32x32x16_bf16 v[48:63], v[72:75], v[232:235], v[48:63]
	s_waitcnt lgkmcnt(10)
	v_mfma_f32_32x32x16_bf16 v[16:31], v[72:75], v[236:239], v[16:31]
	s_waitcnt lgkmcnt(8)
	v_mfma_f32_32x32x16_bf16 v[0:15], v[72:75], v[240:243], v[0:15]
	ds_read_b64_tr_b16 v[72:73], v227 offset:12288
	ds_read_b64_tr_b16 v[74:75], v227 offset:14336
	ds_read_b64_tr_b16 v[92:93], v227 offset:12800
	ds_read_b64_tr_b16 v[94:95], v227 offset:14848
	ds_read_b64_tr_b16 v[228:229], v227 offset:13312
	ds_read_b64_tr_b16 v[230:231], v227 offset:15360
	ds_read_b64_tr_b16 v[232:233], v227 offset:13824
	ds_read_b64_tr_b16 v[234:235], v227 offset:15872
	s_waitcnt lgkmcnt(14)
	v_mfma_f32_32x32x16_bf16 v[32:47], v[68:71], v[76:79], v[32:47]
	s_waitcnt lgkmcnt(12)
	v_mfma_f32_32x32x16_bf16 v[48:63], v[68:71], v[80:83], v[48:63]
	s_waitcnt lgkmcnt(10)
	v_mfma_f32_32x32x16_bf16 v[16:31], v[68:71], v[84:87], v[16:31]
	s_waitcnt lgkmcnt(8)
	v_mfma_f32_32x32x16_bf16 v[0:15], v[68:71], v[88:91], v[0:15]
	s_waitcnt lgkmcnt(6)
	v_mfma_f32_32x32x16_bf16 v[32:47], v[64:67], v[72:75], v[32:47]
	s_waitcnt lgkmcnt(4)
	v_mfma_f32_32x32x16_bf16 v[48:63], v[64:67], v[92:95], v[48:63]
	s_waitcnt lgkmcnt(2)
	v_mfma_f32_32x32x16_bf16 v[16:31], v[64:67], v[228:231], v[16:31]
	s_waitcnt lgkmcnt(0)
	v_mfma_f32_32x32x16_bf16 v[0:15], v[64:67], v[232:235], v[0:15]
	v_add_u32_e32 v68, s14, v218
	ds_read_b128 v[80:83], v68 offset:57344
	v_add_u32_e32 v227, s14, v219
	ds_read_b128 v[64:67], v68 offset:49152
	ds_read_b128 v[232:235], v227 offset:57344
	ds_read_b128 v[228:231], v227 offset:49152
	v_add_u32_e32 v227, s14, v220
	s_waitcnt lgkmcnt(3)
	v_mfma_f32_32x32x16_bf16 v[80:95], v[80:83], v[104:107], v[116:131]
	s_waitcnt lgkmcnt(1)
	v_mfma_f32_32x32x16_bf16 v[80:95], v[232:235], v[108:111], v[80:95]
	ds_read_b128 v[232:235], v227 offset:57344
	v_mfma_f32_32x32x16_bf16 v[64:79], v[64:67], v[104:107], v[116:131]
	s_waitcnt lgkmcnt(1)
	v_mfma_f32_32x32x16_bf16 v[64:79], v[228:231], v[108:111], v[64:79]
	ds_read_b128 v[228:231], v227 offset:49152
	v_add_u32_e32 v227, s14, v221
	s_waitcnt lgkmcnt(1)
	v_mfma_f32_32x32x16_bf16 v[80:95], v[232:235], v[112:115], v[80:95]
	ds_read_b128 v[232:235], v227 offset:57344
	s_waitcnt lgkmcnt(1)
	v_mfma_f32_32x32x16_bf16 v[64:79], v[228:231], v[112:115], v[64:79]
	ds_read_b128 v[228:231], v227 offset:49152
	s_waitcnt lgkmcnt(0)
	v_mfma_f32_32x32x16_bf16 v[64:79], v[228:231], v[100:103], v[64:79]
	v_mfma_f32_32x32x16_bf16 v[80:95], v[232:235], v[100:103], v[80:95]
	s_setprio 0
	s_waitcnt lgkmcnt(0)
	s_barrier
; __device__ __forceinline__ void partialSM(f32x16& p0, f32x16& p1, float& m_reg, float& alpha) {
;   constexpr float THR2 = THR * 1.4426950408889634f;
;   float pmax = p0[0];
; #pragma unroll
;   for (int r = 1; r < 16; ++r) pmax = fmaxf(pmax, p0[r]);
; #pragma unroll
;   for (int r = 0; r < 16; ++r) pmax = fmaxf(pmax, p1[r]);
;   { auto rr = __builtin_amdgcn_permlane32_swap(__float_as_uint(pmax), __float_as_uint(pmax), false, false);
;     pmax = fmaxf(__uint_as_float(rr[0]), __uint_as_float(rr[1])); }
;   float mn;
;   if (__builtin_expect(__all(pmax - m_reg <= THR2), 1)) { mn = m_reg; alpha = 1.f; }
;   else { mn = fmaxf(m_reg, pmax); alpha = __builtin_amdgcn_exp2f(m_reg - mn); m_reg = mn; }
; #pragma unroll
;   for (int r = 0; r < 16; ++r) { p0[r] -= mn; p1[r] -= mn; }
; #pragma unroll
;   for (int r = 0; r < 16; ++r) p0[r] = __builtin_amdgcn_exp2f(p0[r]);
; }
; __device__ __forceinline__ void finishSM(f32x16& p0, f32x16& p1, float alpha, float& l_reg, bf16x8& pa0, bf16x8& pa1, bf16x8& pa2, bf16x8& pa3) {
; #pragma unroll
;   for (int r = 0; r < 16; ++r) p1[r] = __builtin_amdgcn_exp2f(p1[r]);
;   float ps = 0;
; #pragma unroll
;   for (int r = 0; r < 16; ++r) ps += p0[r];
; #pragma unroll
;   for (int r = 0; r < 16; ++r) ps += p1[r];
;   { auto rr = __builtin_amdgcn_permlane32_swap(__float_as_uint(ps), __float_as_uint(ps), false, false);
;     ps = __uint_as_float(rr[0]) + __uint_as_float(rr[1]); }
;   l_reg = l_reg * alpha + ps;
;     ...
;   PK4(p0, 0, pa0); PK4(p0, 8, pa1); PK4(p1, 0, pa2); PK4(p1, 8, pa3);
;     ...
; }
	s_nop 9
	v_max3_f32 v227, v64, v65, v66
	v_max3_f32 v227, v227, v67, v68
	v_max3_f32 v227, v227, v69, v70
	v_max3_f32 v227, v227, v71, v72
	v_max3_f32 v227, v227, v73, v74
	v_max3_f32 v227, v227, v75, v76
	v_max3_f32 v227, v227, v77, v78
	v_max3_f32 v227, v227, v79, v80
	v_max3_f32 v227, v227, v81, v82
	v_max3_f32 v227, v227, v83, v84
	v_max3_f32 v227, v227, v85, v86
	v_max3_f32 v227, v227, v87, v88
	v_max3_f32 v227, v227, v89, v90
	v_max3_f32 v227, v227, v91, v92
	v_max3_f32 v227, v227, v93, v94
	v_max_f32_e32 v227, v227, v95
	v_mov_b32_e32 v228, v227
	s_nop 1
	v_permlane32_swap_b32_e32 v227, v228
	v_max_f32_e32 v227, v227, v228
	v_cmp_ge_f32_e32 vcc, s19, v227
	s_cmp_eq_u64 vcc, exec
	s_cbranch_scc0 .Lw2slow_g1b
	v_exp_f32_e32 v64, v64
	v_exp_f32_e32 v65, v65
	v_exp_f32_e32 v66, v66
	v_add_f32_e32 v246, v65, v64
	v_exp_f32_e32 v67, v67
	v_add_f32_e32 v246, v66, v246
	v_exp_f32_e32 v68, v68
	v_add_f32_e32 v246, v67, v246
	v_exp_f32_e32 v69, v69
	v_add_f32_e32 v246, v68, v246
	v_exp_f32_e32 v70, v70
	v_add_f32_e32 v246, v69, v246
	v_exp_f32_e32 v71, v71
	v_add_f32_e32 v246, v70, v246
	v_exp_f32_e32 v72, v72
	v_add_f32_e32 v246, v71, v246
	v_exp_f32_e32 v73, v73
	v_add_f32_e32 v246, v72, v246
	v_exp_f32_e32 v74, v74
	v_add_f32_e32 v246, v73, v246
	v_exp_f32_e32 v75, v75
	v_add_f32_e32 v246, v74, v246
	v_exp_f32_e32 v228, v76
	v_add_f32_e32 v246, v75, v246
	v_exp_f32_e32 v229, v77
	v_add_f32_e32 v246, v228, v246
	v_exp_f32_e32 v230, v78
	v_add_f32_e32 v246, v229, v246
	v_exp_f32_e32 v231, v79
	v_add_f32_e32 v246, v230, v246
	v_exp_f32_e32 v80, v80
	v_add_f32_e32 v246, v231, v246
	v_exp_f32_e32 v81, v81
	v_add_f32_e32 v246, v80, v246
	v_exp_f32_e32 v82, v82
	v_add_f32_e32 v246, v81, v246
	v_exp_f32_e32 v83, v83
	v_add_f32_e32 v246, v82, v246
	v_exp_f32_e32 v84, v84
	v_add_f32_e32 v246, v83, v246
	v_exp_f32_e32 v85, v85
	v_add_f32_e32 v246, v84, v246
	v_exp_f32_e32 v86, v86
	v_add_f32_e32 v246, v85, v246
	v_exp_f32_e32 v87, v87
	v_add_f32_e32 v246, v86, v246
	v_exp_f32_e32 v88, v88
	v_add_f32_e32 v246, v87, v246
	v_exp_f32_e32 v89, v89
	v_add_f32_e32 v246, v88, v246
	v_exp_f32_e32 v90, v90
	v_add_f32_e32 v246, v89, v246
	v_exp_f32_e32 v91, v91
	v_add_f32_e32 v246, v90, v246
	v_exp_f32_e32 v92, v92
	v_add_f32_e32 v246, v91, v246
	v_exp_f32_e32 v93, v93
	v_add_f32_e32 v246, v92, v246
	v_exp_f32_e32 v94, v94
	v_add_f32_e32 v246, v93, v246
	v_exp_f32_e32 v95, v95
	v_add_f32_e32 v246, v94, v246
	v_cvt_pk_bf16_f32 v76, v64, v65
	v_add_f32_e32 v246, v95, v246
	v_mov_b32_e32 v247, v246
	v_cvt_pk_bf16_f32 v77, v66, v67
	v_cvt_pk_bf16_f32 v78, v68, v69
	v_cvt_pk_bf16_f32 v79, v70, v71
	v_cvt_pk_bf16_f32 v72, v72, v73
	v_cvt_pk_bf16_f32 v73, v74, v75
	v_cvt_pk_bf16_f32 v74, v228, v229
	v_cvt_pk_bf16_f32 v75, v230, v231
	v_cvt_pk_bf16_f32 v68, v80, v81
	v_cvt_pk_bf16_f32 v69, v82, v83
	v_cvt_pk_bf16_f32 v70, v84, v85
	v_cvt_pk_bf16_f32 v71, v86, v87
	v_cvt_pk_bf16_f32 v64, v88, v89
	v_cvt_pk_bf16_f32 v65, v90, v91
	v_cvt_pk_bf16_f32 v66, v92, v93
	v_cvt_pk_bf16_f32 v67, v94, v95
	v_permlane32_swap_b32_e32 v246, v247
	v_add_f32_e32 v222, v222, v246
	v_add_f32_e32 v222, v222, v247

; #define VRDK(L, H, KS) do { _Pragma("unroll") for (int d0 = 0; d0 < 4; ++d0) { L[d0] = vtr(vp + v_rd_off(d0, KS, 0)); H[d0] = vtr(vp + v_rd_off(d0, KS, 1)); } } while (0)
; #define PVK(pa, L, H) do { _Pragma("unroll") for (int d0 = 0; d0 < 4; ++d0) o[d0] = __builtin_amdgcn_mfma_f32_32x32x16_bf16(pa, PK(L[d0], H[d0]), o[d0], 0, 0, 0); } while (0)
; template <int NQ, bool QREG> __device__ __forceinline__ void qkt(f32x16& p0, f32x16& p1, const bf16_t* Ks, const bf16x8* qr, const bf16_t* Qw, int r32, int hi, int qcolB) {
;   p0 = f32x16{}; p1 = f32x16{};
; #pragma unroll
;   for (int d0 = 0; d0 < NQ; ++d0) { int cb = qcolB + (d0 * 16 + hi * 8) * 2;
;     bf16x8 b0 = *reinterpret_cast<const bf16x8*>((const char*)Ks + KSWZ(r32, cb));
;     bf16x8 b1 = *reinterpret_cast<const bf16x8*>((const char*)Ks + KSWZ(32 + r32, cb));
;     const bf16x8 qv = QREG ? qr[d0] : ld8(Qw + d0 * 16);
;     p0 = __builtin_amdgcn_mfma_f32_32x32x16_bf16(b0, qv, p0, 0, 0, 0); p1 = __builtin_amdgcn_mfma_f32_32x32x16_bf16(b1, qv, p1, 0, 0, 0); }
;   if (QREG) { __builtin_amdgcn_sched_group_barrier(0x100, 2 * NQ, 0); __builtin_amdgcn_sched_group_barrier(0x008, 2 * NQ, 0); }
; }
; template <bool PIPE> __device__ __forceinline__ void pv_d0(f32x16* o, lds_cptr vp, bf16x8 pa0, bf16x8 pa1, bf16x8 pa2, bf16x8 pa3) {
;   s16x4 La[4], Ha[4], Lb[4], Hb[4];
;   if constexpr (!PIPE) {
;     VRDK(La, Ha, 0); PVK(pa0, La, Ha); VRDK(La, Ha, 1); PVK(pa1, La, Ha); VRDK(La, Ha, 2); PVK(pa2, La, Ha); VRDK(La, Ha, 3); PVK(pa3, La, Ha);
;     return;
;   }
;   VRDK(La, Ha, 0); VRDK(Lb, Hb, 1);
;   PVK(pa0, La, Ha); VRDK(La, Ha, 2);
;   PVK(pa1, Lb, Hb); VRDK(Lb, Hb, 3);
;   PVK(pa2, La, Ha); PVK(pa3, Lb, Hb);
;   __builtin_amdgcn_sched_group_barrier(0x100, 16, 0); __builtin_amdgcn_sched_group_barrier(0x008, 4, 0);
;   __builtin_amdgcn_sched_group_barrier(0x100, 8, 0);  __builtin_amdgcn_sched_group_barrier(0x008, 4, 0);
;   __builtin_amdgcn_sched_group_barrier(0x100, 8, 0);  __builtin_amdgcn_sched_group_barrier(0x008, 8, 0);
; }
.LBB0_348:
	s_lshl_b32 s13, s10, 14
	s_add_i32 s14, s13, 0
	s_setprio 1
	v_add_u32_e32 v236, s12, v214
	ds_read_b64_tr_b16 v[80:81], v236
	ds_read_b64_tr_b16 v[82:83], v236 offset:2048
	ds_read_b64_tr_b16 v[84:85], v236 offset:512
	ds_read_b64_tr_b16 v[86:87], v236 offset:2560
	ds_read_b64_tr_b16 v[88:89], v236 offset:1024
	ds_read_b64_tr_b16 v[90:91], v236 offset:3072
	ds_read_b64_tr_b16 v[92:93], v236 offset:1536
	ds_read_b64_tr_b16 v[94:95], v236 offset:3584
	ds_read_b64_tr_b16 v[192:193], v236 offset:4096
	ds_read_b64_tr_b16 v[194:195], v236 offset:6144
	ds_read_b64_tr_b16 v[224:225], v236 offset:4608
	ds_read_b64_tr_b16 v[226:227], v236 offset:6656
	ds_read_b64_tr_b16 v[228:229], v236 offset:5120
	ds_read_b64_tr_b16 v[230:231], v236 offset:7168
	ds_read_b64_tr_b16 v[232:233], v236 offset:5632
	ds_read_b64_tr_b16 v[234:235], v236 offset:7680
	s_waitcnt lgkmcnt(14)
	v_mfma_f32_32x32x16_bf16 v[32:47], v[76:79], v[80:83], v[32:47]
	s_waitcnt lgkmcnt(12)
	v_mfma_f32_32x32x16_bf16 v[48:63], v[76:79], v[84:87], v[48:63]
	s_waitcnt lgkmcnt(10)
	v_mfma_f32_32x32x16_bf16 v[16:31], v[76:79], v[88:91], v[16:31]
	s_waitcnt lgkmcnt(8)
	v_mfma_f32_32x32x16_bf16 v[0:15], v[76:79], v[92:95], v[0:15]
	ds_read_b64_tr_b16 v[76:77], v236 offset:8192
	ds_read_b64_tr_b16 v[78:79], v236 offset:10240
	ds_read_b64_tr_b16 v[80:81], v236 offset:8704
	ds_read_b64_tr_b16 v[82:83], v236 offset:10752
	ds_read_b64_tr_b16 v[84:85], v236 offset:9216
	ds_read_b64_tr_b16 v[86:87], v236 offset:11264
	ds_read_b64_tr_b16 v[88:89], v236 offset:9728
	ds_read_b64_tr_b16 v[90:91], v236 offset:11776
	s_waitcnt lgkmcnt(14)
	v_mfma_f32_32x32x16_bf16 v[32:47], v[72:75], v[192:195], v[32:47]
	s_waitcnt lgkmcnt(12)
	v_mfma_f32_32x32x16_bf16 v[48:63], v[72:75], v[224:227], v[48:63]
	s_waitcnt lgkmcnt(10)
	v_mfma_f32_32x32x16_bf16 v[16:31], v[72:75], v[228:231], v[16:31]
	s_waitcnt lgkmcnt(8)
	v_mfma_f32_32x32x16_bf16 v[0:15], v[72:75], v[232:235], v[0:15]
	ds_read_b64_tr_b16 v[72:73], v236 offset:12288
	ds_read_b64_tr_b16 v[74:75], v236 offset:14336
	ds_read_b64_tr_b16 v[92:93], v236 offset:12800
	ds_read_b64_tr_b16 v[94:95], v236 offset:14848
	ds_read_b64_tr_b16 v[192:193], v236 offset:13312
	ds_read_b64_tr_b16 v[194:195], v236 offset:15360
	ds_read_b64_tr_b16 v[224:225], v236 offset:13824
	ds_read_b64_tr_b16 v[226:227], v236 offset:15872
	s_waitcnt lgkmcnt(14)
	v_mfma_f32_32x32x16_bf16 v[32:47], v[68:71], v[76:79], v[32:47]
	s_waitcnt lgkmcnt(12)
	v_mfma_f32_32x32x16_bf16 v[48:63], v[68:71], v[80:83], v[48:63]
	s_waitcnt lgkmcnt(10)
	v_mfma_f32_32x32x16_bf16 v[16:31], v[68:71], v[84:87], v[16:31]
	s_waitcnt lgkmcnt(8)
	v_mfma_f32_32x32x16_bf16 v[0:15], v[68:71], v[88:91], v[0:15]
	s_waitcnt lgkmcnt(6)
	v_mfma_f32_32x32x16_bf16 v[32:47], v[64:67], v[72:75], v[32:47]
	s_waitcnt lgkmcnt(4)
	v_mfma_f32_32x32x16_bf16 v[48:63], v[64:67], v[92:95], v[48:63]
	s_waitcnt lgkmcnt(2)
	v_mfma_f32_32x32x16_bf16 v[16:31], v[64:67], v[192:195], v[16:31]
	s_waitcnt lgkmcnt(0)
	v_mfma_f32_32x32x16_bf16 v[0:15], v[64:67], v[224:227], v[0:15]
	v_add_u32_e32 v68, s14, v218
	ds_read_b128 v[80:83], v68 offset:57344
	ds_read_b128 v[64:67], v68 offset:49152
	v_add_u32_e32 v224, s14, v219
	ds_read_b128 v[192:195], v224 offset:49152
	ds_read_b128 v[224:227], v224 offset:57344
	s_waitcnt lgkmcnt(3)
	v_mfma_f32_32x32x16_bf16 v[80:95], v[80:83], v[104:107], v[116:131]
	s_waitcnt lgkmcnt(2)
	v_mfma_f32_32x32x16_bf16 v[64:79], v[64:67], v[104:107], v[116:131]
	s_waitcnt lgkmcnt(0)
	v_mfma_f32_32x32x16_bf16 v[80:95], v[224:227], v[108:111], v[80:95]
	v_add_u32_e32 v224, s14, v220
	v_mfma_f32_32x32x16_bf16 v[64:79], v[192:195], v[108:111], v[64:79]
	ds_read_b128 v[192:195], v224 offset:49152
	ds_read_b128 v[224:227], v224 offset:57344
	s_waitcnt lgkmcnt(0)
	v_mfma_f32_32x32x16_bf16 v[80:95], v[224:227], v[112:115], v[80:95]
	v_add_u32_e32 v224, s14, v221
	v_mfma_f32_32x32x16_bf16 v[64:79], v[192:195], v[112:115], v[64:79]
	ds_read_b128 v[192:195], v224 offset:49152
	ds_read_b128 v[224:227], v224 offset:57344
	s_waitcnt lgkmcnt(1)
	v_mfma_f32_32x32x16_bf16 v[64:79], v[192:195], v[100:103], v[64:79]
	s_waitcnt lgkmcnt(0)
	v_mfma_f32_32x32x16_bf16 v[80:95], v[224:227], v[100:103], v[80:95]
	s_setprio 0
	s_add_i32 s8, s8, 2
	s_add_u32 s0, s0, 0x240000
	s_waitcnt lgkmcnt(0)
	s_barrier
	s_addc_u32 s1, s1, 0
	s_cmp_ge_u32 s34, s83
	s_cbranch_scc1 .LBB0_350
	s_mov_b32 s12, s10
	s_mov_b32 s10, s11
	s_branch .LBB0_332
; __device__ __forceinline__ void partialSM(f32x16& p0, f32x16& p1, float& m_reg, float& alpha) {
;   constexpr float THR2 = THR * 1.4426950408889634f;
;   float pmax = p0[0];
; #pragma unroll
;   for (int r = 1; r < 16; ++r) pmax = fmaxf(pmax, p0[r]);
; #pragma unroll
;   for (int r = 0; r < 16; ++r) pmax = fmaxf(pmax, p1[r]);
;   { auto rr = __builtin_amdgcn_permlane32_swap(__float_as_uint(pmax), __float_as_uint(pmax), false, false);
;     pmax = fmaxf(__uint_as_float(rr[0]), __uint_as_float(rr[1])); }
;   float mn;
;   if (__builtin_expect(__all(pmax - m_reg <= THR2), 1)) { mn = m_reg; alpha = 1.f; }
;   else { mn = fmaxf(m_reg, pmax); alpha = __builtin_amdgcn_exp2f(m_reg - mn); m_reg = mn; }
; #pragma unroll
;   for (int r = 0; r < 16; ++r) { p0[r] -= mn; p1[r] -= mn; }
; #pragma unroll
;   for (int r = 0; r < 16; ++r) p0[r] = __builtin_amdgcn_exp2f(p0[r]);
; }
.LBB0_350:
	s_waitcnt vmcnt(3)
	s_nop 2
	v_sub_f32_e32 v64, v64, v188
	v_sub_f32_e32 v65, v65, v188
	v_sub_f32_e32 v66, v66, v188
	v_sub_f32_e32 v67, v67, v188
	v_sub_f32_e32 v68, v68, v188
	v_sub_f32_e32 v69, v69, v188
	v_sub_f32_e32 v70, v70, v188
	v_sub_f32_e32 v71, v71, v188
	v_sub_f32_e32 v72, v72, v188
	v_sub_f32_e32 v73, v73, v188
	v_sub_f32_e32 v74, v74, v188
	v_sub_f32_e32 v75, v75, v188
	v_sub_f32_e32 v76, v76, v188
	v_sub_f32_e32 v77, v77, v188
	v_sub_f32_e32 v78, v78, v188
	v_sub_f32_e32 v79, v79, v188
	v_sub_f32_e32 v80, v80, v188
	v_sub_f32_e32 v81, v81, v188
	v_sub_f32_e32 v82, v82, v188
	v_sub_f32_e32 v83, v83, v188
	v_sub_f32_e32 v84, v84, v188
	v_sub_f32_e32 v85, v85, v188
	v_sub_f32_e32 v86, v86, v188
	v_sub_f32_e32 v87, v87, v188
	v_sub_f32_e32 v88, v88, v188
	v_sub_f32_e32 v89, v89, v188
	v_sub_f32_e32 v90, v90, v188
	v_sub_f32_e32 v91, v91, v188
	v_sub_f32_e32 v92, v92, v188
	v_sub_f32_e32 v93, v93, v188
	v_sub_f32_e32 v94, v94, v188
	v_sub_f32_e32 v95, v95, v188
	v_max_f32_e32 v148, v65, v65
	v_max_f32_e32 v149, v64, v64
	v_max_f32_e32 v148, v149, v148
	v_max3_f32 v148, v148, v66, v67
	v_max3_f32 v148, v148, v68, v69
	v_max3_f32 v148, v148, v70, v71
	v_max3_f32 v148, v148, v72, v73
	v_max3_f32 v148, v148, v74, v75
	v_max3_f32 v148, v148, v76, v77
	v_max3_f32 v148, v148, v78, v79
	v_max3_f32 v148, v148, v80, v81
	v_max3_f32 v148, v148, v82, v83
	v_max3_f32 v148, v148, v84, v85
	v_max3_f32 v148, v148, v86, v87
	v_max3_f32 v148, v148, v88, v89
	v_max3_f32 v148, v148, v90, v91
	v_max3_f32 v148, v148, v92, v93
	v_max3_f32 v148, v148, v94, v95
	v_mov_b32_e32 v149, v148
	s_nop 1
	v_permlane32_swap_b32_e32 v148, v149
	v_max_f32_e32 v149, v149, v149
	v_max_f32_e32 v148, v148, v148
	v_max_f32_e32 v148, v148, v149
	v_sub_f32_e32 v149, v148, v223
	v_cmp_ge_f32_e32 vcc, s19, v149
	v_max_f32_e32 v149, v223, v223
	v_max_f32_e32 v149, v149, v148
	v_sub_f32_e32 v148, v223, v149
	v_exp_f32_e32 v148, v148
	s_cmp_eq_u64 vcc, exec
	s_cselect_b64 s[40:41], -1, 0
	v_cndmask_b32_e64 v148, v148, 1.0, s[40:41]
	v_cmp_gt_f32_e32 vcc, 1.0, v148
	s_cbranch_vccz .LBB0_354
	s_and_saveexec_b64 s[0:1], s[38:39]
	ds_write_b32 v213, v148 offset:128
	s_or_b64 exec, exec, s[0:1]
	s_waitcnt lgkmcnt(0)
	s_waitcnt vmcnt(0)
	v_add_u32_e32 v162, s4, v215
	ds_read_b128 v[150:153], v162 offset:224
	ds_read_b128 v[154:157], v162 offset:192
	ds_read_b128 v[158:161], v162 offset:160
	ds_read_b128 v[162:165], v162 offset:128
	s_waitcnt lgkmcnt(3)
	v_pk_mul_f32 v[44:45], v[44:45], v[150:151]
	s_waitcnt lgkmcnt(2)
	v_pk_mul_f32 v[40:41], v[40:41], v[154:155]
	s_waitcnt lgkmcnt(1)
	v_pk_mul_f32 v[36:37], v[36:37], v[158:159]
	v_pk_mul_f32 v[46:47], v[46:47], v[152:153]
	v_pk_mul_f32 v[42:43], v[42:43], v[156:157]
	v_pk_mul_f32 v[38:39], v[38:39], v[160:161]
	s_waitcnt lgkmcnt(0)
	v_pk_mul_f32 v[34:35], v[34:35], v[164:165]
	v_pk_mul_f32 v[32:33], v[32:33], v[162:163]
	v_pk_mul_f32 v[60:61], v[60:61], v[150:151]
	v_pk_mul_f32 v[56:57], v[56:57], v[154:155]
	v_pk_mul_f32 v[52:53], v[52:53], v[158:159]
	v_pk_mul_f32 v[62:63], v[62:63], v[152:153]
	v_pk_mul_f32 v[58:59], v[58:59], v[156:157]
	v_pk_mul_f32 v[54:55], v[54:55], v[160:161]
	v_pk_mul_f32 v[50:51], v[50:51], v[164:165]
	v_pk_mul_f32 v[48:49], v[48:49], v[162:163]
	v_pk_mul_f32 v[28:29], v[28:29], v[150:151]
	v_pk_mul_f32 v[24:25], v[24:25], v[154:155]
	v_pk_mul_f32 v[20:21], v[20:21], v[158:159]
	v_pk_mul_f32 v[30:31], v[30:31], v[152:153]
	v_pk_mul_f32 v[26:27], v[26:27], v[156:157]
	v_pk_mul_f32 v[22:23], v[22:23], v[160:161]
	v_pk_mul_f32 v[18:19], v[18:19], v[164:165]
	v_pk_mul_f32 v[16:17], v[16:17], v[162:163]
	v_pk_mul_f32 v[12:13], v[12:13], v[150:151]
	v_pk_mul_f32 v[8:9], v[8:9], v[154:155]
	v_pk_mul_f32 v[4:5], v[4:5], v[158:159]
	v_pk_mul_f32 v[14:15], v[14:15], v[152:153]
	v_pk_mul_f32 v[10:11], v[10:11], v[156:157]
	v_pk_mul_f32 v[6:7], v[6:7], v[160:161]
	v_pk_mul_f32 v[2:3], v[2:3], v[164:165]
	v_pk_mul_f32 v[0:1], v[0:1], v[162:163]

; __device__ __forceinline__ int v_st(int k, int c) { const int kk = (k & ~0xC) | ((k & 4) << 1) | ((k & 8) >> 1); return ((kk >> 3) * 4 + (c >> 5)) * 512 + ((kk & 7) * 32 + (c & 31)) * 2; }
; __device__ __forceinline__ int v_rd_base(int lane) { return ((lane & 3) << 3) | (((lane >> 2) & 3) << 6) | (((lane >> 4) & 1) << 5) | (((lane >> 5) & 1) << 8); }
; #define SLOAD(S, k0) do { const bf16_t* vt_ = Vh + (long)(k0) * LDK; const bf16_t* kt_ = Kh + (long)(k0) * LDK; \
;     S.vs0 = ld8(vt_ + soff0); S.vs1 = ld8(vt_ + soff1); S.ks0 = ld8(kt_ + soff0); S.ks1 = ld8(kt_ + soff1); } while (0)
; template <int MODE, bool WRITE = true> ...
;     ...
;   const int rg = MODE == 0 ? (wid & 3) : wid, comp = MODE == 0 ? (wid >> 2) : 0;
;   bf16_t* V_lds = (bf16_t*)lds; bf16_t* K_lds = (bf16_t*)(lds + NBUF * SHM_V);
;   float* ws = (float*)(lds + NBUF * SHM_V + NBUF * SHM_K) + wid * 64; float* li_l = ws; float* al_l = ws + 32;
;   float m_run = -1e30f, l_reg = 0.f; f32x16 o[4] = {}; bf16x8 qr[NQ];
;   const bf16_t* Qw = Qb + (long)(rg * QBLK + r32) * LDQ + comp * 64 + hi * 8;
;   const int qcolB = comp * 128;
; #pragma unroll
;   for (int d0 = 0; d0 < NQ; ++d0) qr[d0] = bf16x8{};
;   if (MODE == 0 && have_pre) { qr[0] = pin.q0; qr[1] = pin.q1; qr[2] = pin.q2; qr[3] = pin.q3; }
;   else {
; #pragma unroll
;     for (int d0 = 0; d0 < NQ; ++d0) qr[d0] = ld8(Qw + d0 * 16); }
;   const int sr = tid >> 4, sc = (tid & 15) * 8, vst0 = v_st(sr, sc), vst1 = v_st(32 + sr, sc);
;   const lds_cptr vb0 = (lds_cptr)lds + v_rd_base(lane);
;   Stg stA, stB;
;   const int soff0 = sr * LDK + sc, soff1 = soff0 + 32 * LDK;
;     ...
;   const int grp = wid >> 2;
;   f32x16 p0, p1; float al; bf16x8 pa0, pa1, pa2, pa3; const int NT = seq / KVBLK;
;   if (MODE == 0 && have_pre) { stA.vs0 = pin.vs0; stA.vs1 = pin.vs1; stA.ks0 = pin.ks0; stA.ks1 = pin.ks1; } else { SLOAD(stA, 0); }
;   asm volatile("s_waitcnt vmcnt(0)" ::: "memory"); SWRITE(stA, 0);
;   if constexpr (MODE == 0) { if (have_pre) { stB.vs0 = pin.vb0; stB.vs1 = pin.vb1; stB.ks0 = pin.kb0; stB.ks1 = pin.kb1; } else { SLOAD(stB, KVBLK); } if (2 < NT) SLOAD(stA, 2 * KVBLK); } else { SLOAD(stA, KVBLK); }
;   __syncthreads();
.LBB0_355:
	s_lshl_b32 s0, s7, 1
	s_and_b32 s0, s0, 0x700
	v_or_b32_e32 v0, 32, v215
	s_add_u32 s0, s6, s0
	v_bitop3_b32 v158, v0, v216, v217 bitop3:0xde
	v_or_b32_e32 v0, 64, v215
	s_addc_u32 s1, s5, 0
	v_readlane_b32 s6, v251, 11
	v_bitop3_b32 v159, v0, v216, v217 bitop3:0xde
	v_or_b32_e32 v0, 0x60, v215
	v_readlane_b32 s7, v251, 12
	s_add_u32 s0, s6, s0
	v_mov_b32_e32 v32, v97
	v_mov_b32_e32 v33, v97
	v_mov_b32_e32 v46, v97
	v_mov_b32_e32 v47, v97
	v_bitop3_b32 v160, v0, v216, v217 bitop3:0xde
	s_addc_u32 s1, s7, s1
	v_mov_b32_e32 v34, v97
	v_mov_b32_e32 v35, v97
	v_mov_b32_e32 v36, v97
	v_mov_b32_e32 v37, v97
	v_mov_b32_e32 v38, v97
	v_mov_b32_e32 v39, v97
	v_mov_b32_e32 v40, v97
	v_mov_b32_e32 v41, v97
	v_mov_b32_e32 v42, v97
	v_mov_b32_e32 v43, v97
	v_mov_b32_e32 v44, v97
	v_mov_b32_e32 v45, v97
	v_mov_b64_e32 v[62:63], v[46:47]
	v_mov_b64_e32 v[16:17], v[32:33]
	v_mov_b64_e32 v[0:1], v[32:33]
	v_bitop3_b32 v157, v215, v216, v217 bitop3:0xde
	v_cmp_gt_u32_e64 s[38:39], 32, v99
	s_mov_b32 s9, 2
	s_mov_b32 s8, 1
	v_lshl_add_u64 v[148:149], v[188:189], 1, s[0:1]
	v_lshl_add_u64 v[150:151], v[190:191], 1, s[0:1]
	s_mov_b32 s5, 0
	v_mov_b32_e32 v162, 0xf149f2ca
	v_mov_b32_e32 v156, 0
	s_mov_b64 s[0:1], 0
	v_mov_b64_e32 v[60:61], v[44:45]
	v_mov_b64_e32 v[58:59], v[42:43]
	v_mov_b64_e32 v[56:57], v[40:41]
	v_mov_b64_e32 v[54:55], v[38:39]
	v_mov_b64_e32 v[52:53], v[36:37]
	v_mov_b64_e32 v[50:51], v[34:35]
	v_mov_b64_e32 v[48:49], v[32:33]
	v_mov_b64_e32 v[18:19], v[34:35]
	v_mov_b64_e32 v[20:21], v[36:37]
	v_mov_b64_e32 v[22:23], v[38:39]
	v_mov_b64_e32 v[24:25], v[40:41]
	v_mov_b64_e32 v[26:27], v[42:43]
	v_mov_b64_e32 v[28:29], v[44:45]
	v_mov_b64_e32 v[30:31], v[46:47]
	v_mov_b64_e32 v[2:3], v[34:35]
	v_mov_b64_e32 v[4:5], v[36:37]
	v_mov_b64_e32 v[6:7], v[38:39]
	v_mov_b64_e32 v[8:9], v[40:41]
	v_mov_b64_e32 v[10:11], v[42:43]
	v_mov_b64_e32 v[12:13], v[44:45]
	v_mov_b64_e32 v[14:15], v[46:47]
	s_mov_b32 s7, 0
	v_mov_b32_e32 v232, 0
	v_mov_b32_e32 v233, 0xff800000
	v_mov_b32_e32 v216, 0
	v_mov_b32_e32 v217, 0
	v_mov_b32_e32 v218, 0
	v_mov_b32_e32 v219, 0
	v_mov_b32_e32 v220, 0
	v_mov_b32_e32 v221, 0
	v_mov_b32_e32 v222, 0
	v_mov_b32_e32 v223, 0
	v_mov_b32_e32 v224, 0
	v_mov_b32_e32 v225, 0
	v_mov_b32_e32 v226, 0
	v_mov_b32_e32 v227, 0
	v_mov_b32_e32 v228, 0
	v_mov_b32_e32 v229, 0
	v_mov_b32_e32 v230, 0
	v_mov_b32_e32 v231, 0

; template <int NQ, bool QREG> __device__ __forceinline__ void qkt(f32x16& p0, f32x16& p1, const bf16_t* Ks, const bf16x8* qr, const bf16_t* Qw, int r32, int hi, int qcolB) {
;   p0 = f32x16{}; p1 = f32x16{};
; #pragma unroll
;   for (int d0 = 0; d0 < NQ; ++d0) { int cb = qcolB + (d0 * 16 + hi * 8) * 2;
;     bf16x8 b0 = *reinterpret_cast<const bf16x8*>((const char*)Ks + KSWZ(r32, cb));
;     bf16x8 b1 = *reinterpret_cast<const bf16x8*>((const char*)Ks + KSWZ(32 + r32, cb));
;     const bf16x8 qv = QREG ? qr[d0] : ld8(Qw + d0 * 16);
;     p0 = __builtin_amdgcn_mfma_f32_32x32x16_bf16(b0, qv, p0, 0, 0, 0); p1 = __builtin_amdgcn_mfma_f32_32x32x16_bf16(b1, qv, p1, 0, 0, 0); }
;   if (QREG) { __builtin_amdgcn_sched_group_barrier(0x100, 2 * NQ, 0); __builtin_amdgcn_sched_group_barrier(0x008, 2 * NQ, 0); }
; }
.LBB0_358:
	s_lshl_b32 s10, s6, 14
	s_add_i32 s9, s10, 0
	v_add_u32_e32 v68, s9, v157
	ds_read_b128 v[80:83], v68 offset:57344
	v_add_u32_e32 v161, s9, v158
	ds_read_b128 v[64:67], v68 offset:49152
	ds_read_b128 v[164:167], v161 offset:57344
	ds_read_b128 v[152:155], v161 offset:49152
	v_add_u32_e32 v161, s9, v159
	s_waitcnt lgkmcnt(3)
	v_mfma_f32_32x32x16_bf16 v[80:95], v[80:83], v[104:107], v[216:231]
	s_waitcnt lgkmcnt(1)
	v_mfma_f32_32x32x16_bf16 v[80:95], v[164:167], v[108:111], v[80:95]
	ds_read_b128 v[164:167], v161 offset:57344
	v_mfma_f32_32x32x16_bf16 v[64:79], v[64:67], v[104:107], v[216:231]
	s_waitcnt lgkmcnt(1)
	v_mfma_f32_32x32x16_bf16 v[64:79], v[152:155], v[108:111], v[64:79]
	ds_read_b128 v[152:155], v161 offset:49152
	v_add_u32_e32 v161, s9, v160
	s_waitcnt lgkmcnt(1)
	v_mfma_f32_32x32x16_bf16 v[80:95], v[164:167], v[112:115], v[80:95]
	ds_read_b128 v[164:167], v161 offset:57344
	s_waitcnt lgkmcnt(1)
	v_mfma_f32_32x32x16_bf16 v[64:79], v[152:155], v[112:115], v[64:79]
	ds_read_b128 v[152:155], v161 offset:49152
	s_waitcnt lgkmcnt(0)
	v_mfma_f32_32x32x16_bf16 v[64:79], v[152:155], v[100:103], v[64:79]
	v_mfma_f32_32x32x16_bf16 v[80:95], v[164:167], v[100:103], v[80:95]
	s_setprio 0
	s_add_i32 s9, s7, 1
	s_cmp_ge_u32 s9, s83
	s_cbranch_scc1 .LBB0_360
	s_lshl_b32 s9, s8, 14
	s_add_i32 s9, s9, 0
	v_add_u32_e32 v152, s9, v183
	v_add_u32_e32 v153, s9, v210
	v_add_u32_e32 v154, s9, v211
	v_add_u32_e32 v155, s9, v212
	s_waitcnt vmcnt(3)
	ds_write_b128 v152, v[116:119]
	s_waitcnt vmcnt(1)
	ds_write_b128 v153, v[124:127]
	ds_write_b128 v154, v[120:123] offset:49152
	s_waitcnt vmcnt(0)
	ds_write_b128 v155, v[128:131] offset:49152

; __device__ __forceinline__ void partialSM(f32x16& p0, f32x16& p1, float& m_reg, float& alpha) {
;   constexpr float THR2 = THR * 1.4426950408889634f;
;   float pmax = p0[0];
; #pragma unroll
;   for (int r = 1; r < 16; ++r) pmax = fmaxf(pmax, p0[r]);
; #pragma unroll
;   for (int r = 0; r < 16; ++r) pmax = fmaxf(pmax, p1[r]);
;   { auto rr = __builtin_amdgcn_permlane32_swap(__float_as_uint(pmax), __float_as_uint(pmax), false, false);
;     pmax = fmaxf(__uint_as_float(rr[0]), __uint_as_float(rr[1])); }
;   float mn;
;   if (__builtin_expect(__all(pmax - m_reg <= THR2), 1)) { mn = m_reg; alpha = 1.f; }
;   else { mn = fmaxf(m_reg, pmax); alpha = __builtin_amdgcn_exp2f(m_reg - mn); m_reg = mn; }
; #pragma unroll
;   for (int r = 0; r < 16; ++r) { p0[r] -= mn; p1[r] -= mn; }
; #pragma unroll
;   for (int r = 0; r < 16; ++r) p0[r] = __builtin_amdgcn_exp2f(p0[r]);
; }
; __device__ __forceinline__ void finishSM(f32x16& p0, f32x16& p1, float alpha, float& l_reg, bf16x8& pa0, bf16x8& pa1, bf16x8& pa2, bf16x8& pa3) {
; #pragma unroll
;   for (int r = 0; r < 16; ++r) p1[r] = __builtin_amdgcn_exp2f(p1[r]);
;   float ps = 0;
; #pragma unroll
;   for (int r = 0; r < 16; ++r) ps += p0[r];
; #pragma unroll
;   for (int r = 0; r < 16; ++r) ps += p1[r];
;   { auto rr = __builtin_amdgcn_permlane32_swap(__float_as_uint(ps), __float_as_uint(ps), false, false);
;     ps = __uint_as_float(rr[0]) + __uint_as_float(rr[1]); }
;   l_reg = l_reg * alpha + ps;
;     ...
;   PK4(p0, 0, pa0); PK4(p0, 8, pa1); PK4(p1, 0, pa2); PK4(p1, 8, pa3);
;     ...
; }
.LBB0_362:
	s_nop 1
	v_max3_f32 v161, v64, v65, v66
	v_max3_f32 v161, v161, v67, v68
	v_max3_f32 v161, v161, v69, v70
	v_max3_f32 v161, v161, v71, v72
	v_max3_f32 v161, v161, v73, v74
	v_max3_f32 v161, v161, v75, v76
	v_max3_f32 v161, v161, v77, v78
	v_max3_f32 v161, v161, v79, v80
	v_max3_f32 v161, v161, v81, v82
	v_max3_f32 v161, v161, v83, v84
	v_max3_f32 v161, v161, v85, v86
	v_max3_f32 v161, v161, v87, v88
	v_max3_f32 v161, v161, v89, v90
	v_max3_f32 v161, v161, v91, v92
	v_max3_f32 v161, v161, v93, v94
	v_max_f32_e32 v161, v161, v95
	v_mov_b32_e32 v163, v161
	s_nop 1
	v_permlane32_swap_b32_e32 v161, v163
	v_max_f32_e32 v161, v161, v163
	v_cmp_ge_f32_e32 vcc, v233, v161
	s_cmp_eq_u64 vcc, exec
	s_cbranch_scc0 .Lw2slow_g0a
	v_exp_f32_e32 v64, v64
	v_exp_f32_e32 v65, v65
	v_exp_f32_e32 v66, v66
	v_add_f32_e32 v188, v65, v64
	v_exp_f32_e32 v67, v67
	v_add_f32_e32 v188, v66, v188
	v_exp_f32_e32 v68, v68
	v_add_f32_e32 v188, v67, v188
	v_exp_f32_e32 v69, v69
	v_add_f32_e32 v188, v68, v188
	v_exp_f32_e32 v70, v70
	v_add_f32_e32 v188, v69, v188
	v_exp_f32_e32 v71, v71
	v_add_f32_e32 v188, v70, v188
	v_exp_f32_e32 v72, v72
	v_add_f32_e32 v188, v71, v188
	v_exp_f32_e32 v73, v73
	v_add_f32_e32 v188, v72, v188
	v_exp_f32_e32 v74, v74
	v_add_f32_e32 v188, v73, v188
	v_exp_f32_e32 v75, v75
	v_add_f32_e32 v188, v74, v188
	v_exp_f32_e32 v76, v76
	v_add_f32_e32 v188, v75, v188
	v_exp_f32_e32 v77, v77
	v_add_f32_e32 v188, v76, v188
	v_exp_f32_e32 v78, v78
	v_add_f32_e32 v188, v77, v188
	v_exp_f32_e32 v79, v79
	v_add_f32_e32 v188, v78, v188
	v_exp_f32_e32 v80, v80
	v_add_f32_e32 v188, v79, v188
	v_exp_f32_e32 v81, v81
	v_add_f32_e32 v188, v80, v188
	v_exp_f32_e32 v82, v82
	v_add_f32_e32 v188, v81, v188
	v_exp_f32_e32 v83, v83
	v_add_f32_e32 v188, v82, v188
	v_exp_f32_e32 v84, v84
	v_add_f32_e32 v188, v83, v188
	v_exp_f32_e32 v85, v85
	v_add_f32_e32 v188, v84, v188
	v_exp_f32_e32 v86, v86
	v_add_f32_e32 v188, v85, v188
	v_exp_f32_e32 v87, v87
	v_add_f32_e32 v188, v86, v188
	v_exp_f32_e32 v88, v88
	v_add_f32_e32 v188, v87, v188
	v_exp_f32_e32 v89, v89
	v_add_f32_e32 v188, v88, v188
	v_exp_f32_e32 v90, v90
	v_add_f32_e32 v188, v89, v188
	v_exp_f32_e32 v91, v91
	v_add_f32_e32 v188, v90, v188
	v_exp_f32_e32 v92, v92
	v_add_f32_e32 v188, v91, v188
	v_exp_f32_e32 v93, v93
	v_add_f32_e32 v188, v92, v188
	v_exp_f32_e32 v94, v94
	v_add_f32_e32 v188, v93, v188
	v_exp_f32_e32 v95, v95
	v_add_f32_e32 v188, v94, v188
	v_cvt_pk_bf16_f32 v64, v64, v65
	v_add_f32_e32 v188, v95, v188
	v_mov_b32_e32 v189, v188
	v_cvt_pk_bf16_f32 v65, v66, v67
	v_cvt_pk_bf16_f32 v66, v68, v69
	v_cvt_pk_bf16_f32 v67, v70, v71
	v_cvt_pk_bf16_f32 v68, v72, v73
	v_cvt_pk_bf16_f32 v69, v74, v75
	v_cvt_pk_bf16_f32 v70, v76, v77
	v_cvt_pk_bf16_f32 v71, v78, v79
	v_cvt_pk_bf16_f32 v72, v80, v81
	v_cvt_pk_bf16_f32 v73, v82, v83
	v_cvt_pk_bf16_f32 v74, v84, v85
	v_cvt_pk_bf16_f32 v75, v86, v87
	v_cvt_pk_bf16_f32 v76, v88, v89
	v_cvt_pk_bf16_f32 v77, v90, v91
	v_cvt_pk_bf16_f32 v78, v92, v93
	v_cvt_pk_bf16_f32 v79, v94, v95
	v_permlane32_swap_b32_e32 v188, v189
	v_add_f32_e32 v156, v156, v188
	v_add_f32_e32 v156, v156, v189
; #define VRDK(L, H, KS) do { _Pragma("unroll") for (int d0 = 0; d0 < 4; ++d0) { L[d0] = vtr(vp + v_rd_off(d0, KS, 0)); H[d0] = vtr(vp + v_rd_off(d0, KS, 1)); } } while (0)
; #define PVK(pa, L, H) do { _Pragma("unroll") for (int d0 = 0; d0 < 4; ++d0) o[d0] = __builtin_amdgcn_mfma_f32_32x32x16_bf16(pa, PK(L[d0], H[d0]), o[d0], 0, 0, 0); } while (0)
; template <int NQ, bool QREG> __device__ __forceinline__ void qkt(f32x16& p0, f32x16& p1, const bf16_t* Ks, const bf16x8* qr, const bf16_t* Qw, int r32, int hi, int qcolB) {
;   p0 = f32x16{}; p1 = f32x16{};
; #pragma unroll
;   for (int d0 = 0; d0 < NQ; ++d0) { int cb = qcolB + (d0 * 16 + hi * 8) * 2;
;     bf16x8 b0 = *reinterpret_cast<const bf16x8*>((const char*)Ks + KSWZ(r32, cb));
;     bf16x8 b1 = *reinterpret_cast<const bf16x8*>((const char*)Ks + KSWZ(32 + r32, cb));
;     const bf16x8 qv = QREG ? qr[d0] : ld8(Qw + d0 * 16);
;     p0 = __builtin_amdgcn_mfma_f32_32x32x16_bf16(b0, qv, p0, 0, 0, 0); p1 = __builtin_amdgcn_mfma_f32_32x32x16_bf16(b1, qv, p1, 0, 0, 0); }
;   if (QREG) { __builtin_amdgcn_sched_group_barrier(0x100, 2 * NQ, 0); __builtin_amdgcn_sched_group_barrier(0x008, 2 * NQ, 0); }
; }
; template <bool PIPE> __device__ __forceinline__ void pv_d0(f32x16* o, lds_cptr vp, bf16x8 pa0, bf16x8 pa1, bf16x8 pa2, bf16x8 pa3) {
;   s16x4 La[4], Ha[4], Lb[4], Hb[4];
;   if constexpr (!PIPE) {
;     VRDK(La, Ha, 0); PVK(pa0, La, Ha); VRDK(La, Ha, 1); PVK(pa1, La, Ha); VRDK(La, Ha, 2); PVK(pa2, La, Ha); VRDK(La, Ha, 3); PVK(pa3, La, Ha);
;     return;
;   }
;   VRDK(La, Ha, 0); VRDK(Lb, Hb, 1);
;   PVK(pa0, La, Ha); VRDK(La, Ha, 2);
;   PVK(pa1, Lb, Hb); VRDK(Lb, Hb, 3);
;   PVK(pa2, La, Ha); PVK(pa3, Lb, Hb);
;   __builtin_amdgcn_sched_group_barrier(0x100, 16, 0); __builtin_amdgcn_sched_group_barrier(0x008, 4, 0);
;   __builtin_amdgcn_sched_group_barrier(0x100, 8, 0);  __builtin_amdgcn_sched_group_barrier(0x008, 4, 0);
;   __builtin_amdgcn_sched_group_barrier(0x100, 8, 0);  __builtin_amdgcn_sched_group_barrier(0x008, 8, 0);
; }
.Lw2join_g0a:
	s_waitcnt lgkmcnt(0)
	s_barrier
	s_lshl_b32 s9, s8, 14
	s_add_i32 s11, s9, 0
	s_setprio 1
	v_add_u32_e32 v165, s10, v214
	ds_read_b64_tr_b16 v[80:81], v165
	ds_read_b64_tr_b16 v[82:83], v165 offset:2048
	ds_read_b64_tr_b16 v[84:85], v165 offset:512
	ds_read_b64_tr_b16 v[86:87], v165 offset:2560
	ds_read_b64_tr_b16 v[88:89], v165 offset:1024
	ds_read_b64_tr_b16 v[90:91], v165 offset:3072
	ds_read_b64_tr_b16 v[92:93], v165 offset:1536
	ds_read_b64_tr_b16 v[94:95], v165 offset:3584
	ds_read_b64_tr_b16 v[166:167], v165 offset:4096
	ds_read_b64_tr_b16 v[168:169], v165 offset:6144
	ds_read_b64_tr_b16 v[170:171], v165 offset:4608
	ds_read_b64_tr_b16 v[172:173], v165 offset:6656
	ds_read_b64_tr_b16 v[174:175], v165 offset:5120
	ds_read_b64_tr_b16 v[176:177], v165 offset:7168
	ds_read_b64_tr_b16 v[188:189], v165 offset:5632
	ds_read_b64_tr_b16 v[190:191], v165 offset:7680
	s_waitcnt lgkmcnt(14)
	v_mfma_f32_32x32x16_bf16 v[32:47], v[64:67], v[80:83], v[32:47]
	s_waitcnt lgkmcnt(12)
	v_mfma_f32_32x32x16_bf16 v[48:63], v[64:67], v[84:87], v[48:63]
	s_waitcnt lgkmcnt(10)
	v_mfma_f32_32x32x16_bf16 v[16:31], v[64:67], v[88:91], v[16:31]
	s_waitcnt lgkmcnt(8)
	v_mfma_f32_32x32x16_bf16 v[0:15], v[64:67], v[92:95], v[0:15]
	ds_read_b64_tr_b16 v[64:65], v165 offset:8192
	ds_read_b64_tr_b16 v[66:67], v165 offset:10240
	ds_read_b64_tr_b16 v[80:81], v165 offset:8704
	ds_read_b64_tr_b16 v[82:83], v165 offset:10752
	ds_read_b64_tr_b16 v[84:85], v165 offset:9216
	ds_read_b64_tr_b16 v[86:87], v165 offset:11264
	ds_read_b64_tr_b16 v[88:89], v165 offset:9728
	ds_read_b64_tr_b16 v[90:91], v165 offset:11776
	s_waitcnt lgkmcnt(14)
	v_mfma_f32_32x32x16_bf16 v[32:47], v[68:71], v[166:169], v[32:47]
	s_waitcnt lgkmcnt(12)
	v_mfma_f32_32x32x16_bf16 v[48:63], v[68:71], v[170:173], v[48:63]
	s_waitcnt lgkmcnt(10)
	v_mfma_f32_32x32x16_bf16 v[16:31], v[68:71], v[174:177], v[16:31]
	s_waitcnt lgkmcnt(8)
	v_mfma_f32_32x32x16_bf16 v[0:15], v[68:71], v[188:191], v[0:15]
	ds_read_b64_tr_b16 v[68:69], v165 offset:12288
	ds_read_b64_tr_b16 v[70:71], v165 offset:14336
	ds_read_b64_tr_b16 v[92:93], v165 offset:12800
	ds_read_b64_tr_b16 v[94:95], v165 offset:14848
	ds_read_b64_tr_b16 v[166:167], v165 offset:13312
	ds_read_b64_tr_b16 v[168:169], v165 offset:15360
	ds_read_b64_tr_b16 v[170:171], v165 offset:13824
	ds_read_b64_tr_b16 v[172:173], v165 offset:15872
	s_waitcnt lgkmcnt(14)
	v_mfma_f32_32x32x16_bf16 v[32:47], v[72:75], v[64:67], v[32:47]
	s_waitcnt lgkmcnt(12)
	v_mfma_f32_32x32x16_bf16 v[48:63], v[72:75], v[80:83], v[48:63]
	s_waitcnt lgkmcnt(10)
	v_mfma_f32_32x32x16_bf16 v[16:31], v[72:75], v[84:87], v[16:31]
	s_waitcnt lgkmcnt(8)
	v_mfma_f32_32x32x16_bf16 v[0:15], v[72:75], v[88:91], v[0:15]
	s_waitcnt lgkmcnt(6)
	v_mfma_f32_32x32x16_bf16 v[32:47], v[76:79], v[68:71], v[32:47]
	s_waitcnt lgkmcnt(4)
	v_mfma_f32_32x32x16_bf16 v[48:63], v[76:79], v[92:95], v[48:63]
	s_waitcnt lgkmcnt(2)
	v_mfma_f32_32x32x16_bf16 v[16:31], v[76:79], v[166:169], v[16:31]
	s_waitcnt lgkmcnt(0)
	v_mfma_f32_32x32x16_bf16 v[0:15], v[76:79], v[170:173], v[0:15]
	v_add_u32_e32 v68, s11, v157
	ds_read_b128 v[80:83], v68 offset:57344
	v_add_u32_e32 v165, s11, v158
	ds_read_b128 v[64:67], v68 offset:49152
	ds_read_b128 v[170:173], v165 offset:57344
	ds_read_b128 v[166:169], v165 offset:49152
	v_add_u32_e32 v165, s11, v159
	s_waitcnt lgkmcnt(3)
	v_mfma_f32_32x32x16_bf16 v[80:95], v[80:83], v[104:107], v[216:231]
	s_waitcnt lgkmcnt(1)
	v_mfma_f32_32x32x16_bf16 v[80:95], v[170:173], v[108:111], v[80:95]
	ds_read_b128 v[170:173], v165 offset:57344
	v_mfma_f32_32x32x16_bf16 v[64:79], v[64:67], v[104:107], v[216:231]
	s_waitcnt lgkmcnt(1)
	v_mfma_f32_32x32x16_bf16 v[64:79], v[166:169], v[108:111], v[64:79]
	ds_read_b128 v[166:169], v165 offset:49152
	v_add_u32_e32 v165, s11, v160
	s_waitcnt lgkmcnt(1)
	v_mfma_f32_32x32x16_bf16 v[80:95], v[170:173], v[112:115], v[80:95]
	ds_read_b128 v[170:173], v165 offset:57344
	s_waitcnt lgkmcnt(1)
	v_mfma_f32_32x32x16_bf16 v[64:79], v[166:169], v[112:115], v[64:79]
	ds_read_b128 v[166:169], v165 offset:49152
	s_waitcnt lgkmcnt(0)
	v_mfma_f32_32x32x16_bf16 v[64:79], v[166:169], v[100:103], v[64:79]
	v_mfma_f32_32x32x16_bf16 v[80:95], v[170:173], v[100:103], v[80:95]
	s_setprio 0
	s_add_i32 s10, s7, 2
	s_cmp_ge_u32 s10, s83
	s_cselect_b64 s[34:35], -1, 0
	s_and_b64 vcc, exec, s[34:35]
	s_cbranch_vccnz .LBB0_368
	s_lshl_b32 s11, s5, 14
	s_add_i32 s11, s11, 0
	v_add_u32_e32 v165, s11, v183
	v_add_u32_e32 v166, s11, v210
	v_add_u32_e32 v167, s11, v211
	v_add_u32_e32 v168, s11, v212
	s_waitcnt vmcnt(3)
	ds_write_b128 v165, v[132:135]
	s_waitcnt vmcnt(1)
	ds_write_b128 v166, v[136:139]
	s_waitcnt vmcnt(1)
	ds_write_b128 v167, v[140:143] offset:49152
	s_waitcnt vmcnt(0)
	ds_write_b128 v168, v[144:147] offset:49152

; __device__ __forceinline__ void partialSM(f32x16& p0, f32x16& p1, float& m_reg, float& alpha) {
;   constexpr float THR2 = THR * 1.4426950408889634f;
;   float pmax = p0[0];
; #pragma unroll
;   for (int r = 1; r < 16; ++r) pmax = fmaxf(pmax, p0[r]);
; #pragma unroll
;   for (int r = 0; r < 16; ++r) pmax = fmaxf(pmax, p1[r]);
;   { auto rr = __builtin_amdgcn_permlane32_swap(__float_as_uint(pmax), __float_as_uint(pmax), false, false);
;     pmax = fmaxf(__uint_as_float(rr[0]), __uint_as_float(rr[1])); }
;   float mn;
;   if (__builtin_expect(__all(pmax - m_reg <= THR2), 1)) { mn = m_reg; alpha = 1.f; }
;   else { mn = fmaxf(m_reg, pmax); alpha = __builtin_amdgcn_exp2f(m_reg - mn); m_reg = mn; }
; #pragma unroll
;   for (int r = 0; r < 16; ++r) { p0[r] -= mn; p1[r] -= mn; }
; #pragma unroll
;   for (int r = 0; r < 16; ++r) p0[r] = __builtin_amdgcn_exp2f(p0[r]);
; }
; __device__ __forceinline__ void finishSM(f32x16& p0, f32x16& p1, float alpha, float& l_reg, bf16x8& pa0, bf16x8& pa1, bf16x8& pa2, bf16x8& pa3) {
; #pragma unroll
;   for (int r = 0; r < 16; ++r) p1[r] = __builtin_amdgcn_exp2f(p1[r]);
;   float ps = 0;
; #pragma unroll
;   for (int r = 0; r < 16; ++r) ps += p0[r];
; #pragma unroll
;   for (int r = 0; r < 16; ++r) ps += p1[r];
;   { auto rr = __builtin_amdgcn_permlane32_swap(__float_as_uint(ps), __float_as_uint(ps), false, false);
;     ps = __uint_as_float(rr[0]) + __uint_as_float(rr[1]); }
;   l_reg = l_reg * alpha + ps;
;     ...
;   PK4(p0, 0, pa0); PK4(p0, 8, pa1); PK4(p1, 0, pa2); PK4(p1, 8, pa3);
;     ...
; }
.LBB0_370:
	s_nop 1
	v_max3_f32 v152, v64, v65, v66
	v_max3_f32 v152, v152, v67, v68
	v_max3_f32 v152, v152, v69, v70
	v_max3_f32 v152, v152, v71, v72
	v_max3_f32 v152, v152, v73, v74
	v_max3_f32 v152, v152, v75, v76
	v_max3_f32 v152, v152, v77, v78
	v_max3_f32 v152, v152, v79, v80
	v_max3_f32 v152, v152, v81, v82
	v_max3_f32 v152, v152, v83, v84
	v_max3_f32 v152, v152, v85, v86
	v_max3_f32 v152, v152, v87, v88
	v_max3_f32 v152, v152, v89, v90
	v_max3_f32 v152, v152, v91, v92
	v_max3_f32 v152, v152, v93, v94
	v_max_f32_e32 v152, v152, v95
	v_mov_b32_e32 v153, v152
	s_nop 1
	v_permlane32_swap_b32_e32 v152, v153
	v_max_f32_e32 v152, v152, v153
	v_cmp_ge_f32_e32 vcc, v233, v152
	s_cmp_eq_u64 vcc, exec
	s_cbranch_scc0 .Lw2slow_g0b
	v_exp_f32_e32 v64, v64
	v_exp_f32_e32 v65, v65
	v_exp_f32_e32 v66, v66
	v_add_f32_e32 v190, v65, v64
	v_exp_f32_e32 v67, v67
	v_add_f32_e32 v190, v66, v190
	v_exp_f32_e32 v68, v68
	v_add_f32_e32 v190, v67, v190
	v_exp_f32_e32 v69, v69
	v_add_f32_e32 v190, v68, v190
	v_exp_f32_e32 v70, v70
	v_add_f32_e32 v190, v69, v190
	v_exp_f32_e32 v71, v71
	v_add_f32_e32 v190, v70, v190
	v_exp_f32_e32 v72, v72
	v_add_f32_e32 v190, v71, v190
	v_exp_f32_e32 v73, v73
	v_add_f32_e32 v190, v72, v190
	v_exp_f32_e32 v74, v74
	v_add_f32_e32 v190, v73, v190
	v_exp_f32_e32 v75, v75
	v_add_f32_e32 v190, v74, v190
	v_exp_f32_e32 v153, v76
	v_add_f32_e32 v190, v75, v190
	v_exp_f32_e32 v154, v77
	v_add_f32_e32 v190, v153, v190
	v_exp_f32_e32 v155, v78
	v_add_f32_e32 v190, v154, v190
	v_exp_f32_e32 v165, v79
	v_add_f32_e32 v190, v155, v190
	v_exp_f32_e32 v80, v80
	v_add_f32_e32 v190, v165, v190
	v_exp_f32_e32 v81, v81
	v_add_f32_e32 v190, v80, v190
	v_exp_f32_e32 v82, v82
	v_add_f32_e32 v190, v81, v190
	v_exp_f32_e32 v83, v83
	v_add_f32_e32 v190, v82, v190
	v_exp_f32_e32 v84, v84
	v_add_f32_e32 v190, v83, v190
	v_exp_f32_e32 v85, v85
	v_add_f32_e32 v190, v84, v190
	v_exp_f32_e32 v86, v86
	v_add_f32_e32 v190, v85, v190
	v_exp_f32_e32 v87, v87
	v_add_f32_e32 v190, v86, v190
	v_exp_f32_e32 v88, v88
	v_add_f32_e32 v190, v87, v190
	v_exp_f32_e32 v89, v89
	v_add_f32_e32 v190, v88, v190
	v_exp_f32_e32 v90, v90
	v_add_f32_e32 v190, v89, v190
	v_exp_f32_e32 v91, v91
	v_add_f32_e32 v190, v90, v190
	v_exp_f32_e32 v92, v92
	v_add_f32_e32 v190, v91, v190
	v_exp_f32_e32 v93, v93
	v_add_f32_e32 v190, v92, v190
	v_exp_f32_e32 v94, v94
	v_add_f32_e32 v190, v93, v190
	v_exp_f32_e32 v95, v95
	v_add_f32_e32 v190, v94, v190
	v_cvt_pk_bf16_f32 v76, v64, v65
	v_add_f32_e32 v190, v95, v190
	v_mov_b32_e32 v191, v190
	v_cvt_pk_bf16_f32 v77, v66, v67
	v_cvt_pk_bf16_f32 v78, v68, v69
	v_cvt_pk_bf16_f32 v79, v70, v71
	v_cvt_pk_bf16_f32 v72, v72, v73
	v_cvt_pk_bf16_f32 v73, v74, v75
	v_cvt_pk_bf16_f32 v74, v153, v154
	v_cvt_pk_bf16_f32 v75, v155, v165
	v_cvt_pk_bf16_f32 v68, v80, v81
	v_cvt_pk_bf16_f32 v69, v82, v83
	v_cvt_pk_bf16_f32 v70, v84, v85
	v_cvt_pk_bf16_f32 v71, v86, v87
	v_cvt_pk_bf16_f32 v64, v88, v89
	v_cvt_pk_bf16_f32 v65, v90, v91
	v_cvt_pk_bf16_f32 v66, v92, v93
	v_cvt_pk_bf16_f32 v67, v94, v95
	v_permlane32_swap_b32_e32 v190, v191
	v_add_f32_e32 v156, v156, v190
	v_add_f32_e32 v156, v156, v191

; __device__ __forceinline__ void partialSM(f32x16& p0, f32x16& p1, float& m_reg, float& alpha) {
;   constexpr float THR2 = THR * 1.4426950408889634f;
;   float pmax = p0[0];
; #pragma unroll
;   for (int r = 1; r < 16; ++r) pmax = fmaxf(pmax, p0[r]);
; #pragma unroll
;   for (int r = 0; r < 16; ++r) pmax = fmaxf(pmax, p1[r]);
;   { auto rr = __builtin_amdgcn_permlane32_swap(__float_as_uint(pmax), __float_as_uint(pmax), false, false);
;     pmax = fmaxf(__uint_as_float(rr[0]), __uint_as_float(rr[1])); }
;   float mn;
;   if (__builtin_expect(__all(pmax - m_reg <= THR2), 1)) { mn = m_reg; alpha = 1.f; }
;   else { mn = fmaxf(m_reg, pmax); alpha = __builtin_amdgcn_exp2f(m_reg - mn); m_reg = mn; }
; #pragma unroll
;   for (int r = 0; r < 16; ++r) { p0[r] -= mn; p1[r] -= mn; }
; #pragma unroll
;   for (int r = 0; r < 16; ++r) p0[r] = __builtin_amdgcn_exp2f(p0[r]);
; }
; __device__ __forceinline__ void finishSM(f32x16& p0, f32x16& p1, float alpha, float& l_reg, bf16x8& pa0, bf16x8& pa1, bf16x8& pa2, bf16x8& pa3) {
; #pragma unroll
;   for (int r = 0; r < 16; ++r) p1[r] = __builtin_amdgcn_exp2f(p1[r]);
;   float ps = 0;
; #pragma unroll
;   for (int r = 0; r < 16; ++r) ps += p0[r];
; #pragma unroll
;   for (int r = 0; r < 16; ++r) ps += p1[r];
;   { auto rr = __builtin_amdgcn_permlane32_swap(__float_as_uint(ps), __float_as_uint(ps), false, false);
;     ps = __uint_as_float(rr[0]) + __uint_as_float(rr[1]); }
;   l_reg = l_reg * alpha + ps;
;     ...
;   PK4(p0, 0, pa0); PK4(p0, 8, pa1); PK4(p1, 0, pa2); PK4(p1, 8, pa3);
;     ...
; }
.Lw2slow_g1a:
	v_sub_f32_e32 v192, v192, v188
	v_max_f32_e32 v193, v223, v192
	v_sub_f32_e32 v192, v223, v193
	v_exp_f32_e32 v192, v192
	v_mov_b32_e32 v223, v193
	v_add_f32_e32 v224, v188, v193
	v_sub_f32_e32 v188, 0, v223
	v_mov_b32_e32 v116, v188
	v_mov_b32_e32 v117, v188
	v_mov_b32_e32 v118, v188
	v_mov_b32_e32 v119, v188
	v_mov_b32_e32 v120, v188
	v_mov_b32_e32 v121, v188
	v_mov_b32_e32 v122, v188
	v_mov_b32_e32 v123, v188
	v_mov_b32_e32 v124, v188
	v_mov_b32_e32 v125, v188
	v_mov_b32_e32 v126, v188
	v_mov_b32_e32 v127, v188
	v_mov_b32_e32 v128, v188
	v_mov_b32_e32 v129, v188
	v_mov_b32_e32 v130, v188
	v_mov_b32_e32 v131, v188
	s_and_saveexec_b64 s[72:73], s[38:39]
	ds_write_b32 v213, v192 offset:128
	s_or_b64 exec, exec, s[72:73]
	s_waitcnt lgkmcnt(0)
	v_add_u32_e32 v194, s4, v215
	ds_read_b128 v[226:229], v194 offset:224
	ds_read_b128 v[230:233], v194 offset:192
	ds_read_b128 v[234:237], v194 offset:160
	ds_read_b128 v[238:241], v194 offset:128
	s_waitcnt lgkmcnt(0)
	v_pk_mul_f32 v[44:45], v[44:45], v[226:227]
	v_pk_mul_f32 v[40:41], v[40:41], v[230:231]
	v_pk_mul_f32 v[36:37], v[36:37], v[234:235]
	v_pk_mul_f32 v[46:47], v[46:47], v[228:229]
	v_pk_mul_f32 v[42:43], v[42:43], v[232:233]
	v_pk_mul_f32 v[38:39], v[38:39], v[236:237]
	v_pk_mul_f32 v[34:35], v[34:35], v[240:241]
	v_pk_mul_f32 v[32:33], v[32:33], v[238:239]
	v_pk_mul_f32 v[60:61], v[60:61], v[226:227]
	v_pk_mul_f32 v[56:57], v[56:57], v[230:231]
	v_pk_mul_f32 v[52:53], v[52:53], v[234:235]
	v_pk_mul_f32 v[62:63], v[62:63], v[228:229]
	v_pk_mul_f32 v[58:59], v[58:59], v[232:233]
	v_pk_mul_f32 v[54:55], v[54:55], v[236:237]
	v_pk_mul_f32 v[50:51], v[50:51], v[240:241]
	v_pk_mul_f32 v[48:49], v[48:49], v[238:239]
	v_pk_mul_f32 v[28:29], v[28:29], v[226:227]
	v_pk_mul_f32 v[24:25], v[24:25], v[230:231]
	v_pk_mul_f32 v[20:21], v[20:21], v[234:235]
	v_pk_mul_f32 v[30:31], v[30:31], v[228:229]
	v_pk_mul_f32 v[26:27], v[26:27], v[232:233]
	v_pk_mul_f32 v[22:23], v[22:23], v[236:237]
	v_pk_mul_f32 v[18:19], v[18:19], v[240:241]
	v_pk_mul_f32 v[16:17], v[16:17], v[238:239]
	v_pk_mul_f32 v[12:13], v[12:13], v[226:227]
	v_pk_mul_f32 v[8:9], v[8:9], v[230:231]
	v_pk_mul_f32 v[4:5], v[4:5], v[234:235]
	v_pk_mul_f32 v[14:15], v[14:15], v[228:229]
	v_pk_mul_f32 v[10:11], v[10:11], v[232:233]
	v_pk_mul_f32 v[6:7], v[6:7], v[236:237]
	v_pk_mul_f32 v[2:3], v[2:3], v[240:241]
	v_pk_mul_f32 v[0:1], v[0:1], v[238:239]
	v_mul_f32_e32 v222, v222, v192
	v_sub_f32_e32 v64, v64, v224
	v_exp_f32_e32 v64, v64
	v_sub_f32_e32 v65, v65, v224
	v_exp_f32_e32 v65, v65
	v_sub_f32_e32 v66, v66, v224
	v_exp_f32_e32 v66, v66
	v_add_f32_e32 v225, v65, v64
	v_sub_f32_e32 v67, v67, v224
	v_exp_f32_e32 v67, v67
	v_add_f32_e32 v225, v66, v225
	v_sub_f32_e32 v68, v68, v224
	v_exp_f32_e32 v68, v68
	v_add_f32_e32 v225, v67, v225
	v_sub_f32_e32 v69, v69, v224
	v_exp_f32_e32 v69, v69
	v_add_f32_e32 v225, v68, v225
	v_sub_f32_e32 v70, v70, v224
	v_exp_f32_e32 v70, v70
	v_add_f32_e32 v225, v69, v225
	v_sub_f32_e32 v71, v71, v224
	v_exp_f32_e32 v71, v71
	v_add_f32_e32 v225, v70, v225
	v_sub_f32_e32 v72, v72, v224
	v_exp_f32_e32 v72, v72
	v_add_f32_e32 v225, v71, v225
	v_sub_f32_e32 v73, v73, v224
	v_exp_f32_e32 v73, v73
	v_add_f32_e32 v225, v72, v225
	v_sub_f32_e32 v74, v74, v224
	v_exp_f32_e32 v74, v74
	v_add_f32_e32 v225, v73, v225
	v_sub_f32_e32 v75, v75, v224
	v_exp_f32_e32 v75, v75
	v_add_f32_e32 v225, v74, v225
	v_sub_f32_e32 v76, v76, v224
	v_exp_f32_e32 v192, v76
	v_add_f32_e32 v225, v75, v225
	v_sub_f32_e32 v77, v77, v224
	v_exp_f32_e32 v193, v77
	v_add_f32_e32 v225, v192, v225
	v_sub_f32_e32 v78, v78, v224
	v_exp_f32_e32 v194, v78
	v_add_f32_e32 v225, v193, v225
	v_sub_f32_e32 v79, v79, v224
	v_exp_f32_e32 v195, v79
	v_add_f32_e32 v225, v194, v225
	v_sub_f32_e32 v80, v80, v224
	v_exp_f32_e32 v80, v80
	v_add_f32_e32 v225, v195, v225
	v_sub_f32_e32 v81, v81, v224
	v_exp_f32_e32 v81, v81
	v_add_f32_e32 v225, v80, v225
	v_sub_f32_e32 v82, v82, v224
	v_exp_f32_e32 v82, v82
	v_add_f32_e32 v225, v81, v225
	v_sub_f32_e32 v83, v83, v224
	v_exp_f32_e32 v83, v83
	v_add_f32_e32 v225, v82, v225
	v_sub_f32_e32 v84, v84, v224
	v_exp_f32_e32 v84, v84
	v_add_f32_e32 v225, v83, v225
	v_sub_f32_e32 v85, v85, v224
	v_exp_f32_e32 v85, v85
	v_add_f32_e32 v225, v84, v225
	v_sub_f32_e32 v86, v86, v224
	v_exp_f32_e32 v86, v86
	v_add_f32_e32 v225, v85, v225
	v_sub_f32_e32 v87, v87, v224
	v_exp_f32_e32 v87, v87
	v_add_f32_e32 v225, v86, v225
	v_sub_f32_e32 v88, v88, v224
	v_exp_f32_e32 v88, v88
	v_add_f32_e32 v225, v87, v225
	v_sub_f32_e32 v89, v89, v224
	v_exp_f32_e32 v89, v89
	v_add_f32_e32 v225, v88, v225
	v_sub_f32_e32 v90, v90, v224
	v_exp_f32_e32 v90, v90
	v_add_f32_e32 v225, v89, v225
	v_sub_f32_e32 v91, v91, v224
	v_exp_f32_e32 v91, v91
	v_add_f32_e32 v225, v90, v225
	v_sub_f32_e32 v92, v92, v224
	v_exp_f32_e32 v92, v92
	v_add_f32_e32 v225, v91, v225
	v_sub_f32_e32 v93, v93, v224
	v_exp_f32_e32 v93, v93
	v_add_f32_e32 v225, v92, v225
	v_sub_f32_e32 v94, v94, v224
	v_exp_f32_e32 v94, v94
	v_add_f32_e32 v225, v93, v225
	v_sub_f32_e32 v95, v95, v224
	v_exp_f32_e32 v95, v95
	v_add_f32_e32 v225, v94, v225
	v_cvt_pk_bf16_f32 v76, v64, v65
	v_add_f32_e32 v225, v95, v225
	v_mov_b32_e32 v226, v225
	v_cvt_pk_bf16_f32 v77, v66, v67
	v_cvt_pk_bf16_f32 v78, v68, v69
	v_cvt_pk_bf16_f32 v79, v70, v71
	v_cvt_pk_bf16_f32 v72, v72, v73
	v_cvt_pk_bf16_f32 v73, v74, v75
	v_cvt_pk_bf16_f32 v74, v192, v193
	v_cvt_pk_bf16_f32 v75, v194, v195
	v_cvt_pk_bf16_f32 v68, v80, v81
	v_cvt_pk_bf16_f32 v69, v82, v83
	v_cvt_pk_bf16_f32 v70, v84, v85
	v_cvt_pk_bf16_f32 v71, v86, v87
	v_cvt_pk_bf16_f32 v64, v88, v89
	v_cvt_pk_bf16_f32 v65, v90, v91
	v_cvt_pk_bf16_f32 v66, v92, v93
	v_cvt_pk_bf16_f32 v67, v94, v95
	v_permlane32_swap_b32_e32 v225, v226
	v_add_f32_e32 v222, v222, v225
	v_add_f32_e32 v222, v222, v226
	s_branch .Lw2join_g1a
; __device__ __forceinline__ void partialSM(f32x16& p0, f32x16& p1, float& m_reg, float& alpha) {
;     ...
;   if (__builtin_expect(__all(pmax - m_reg <= THR2), 1)) { mn = m_reg; alpha = 1.f; }
;   else { mn = fmaxf(m_reg, pmax); alpha = __builtin_amdgcn_exp2f(m_reg - mn); m_reg = mn; }
; #pragma unroll
;   for (int r = 0; r < 16; ++r) { p0[r] -= mn; p1[r] -= mn; }
; #pragma unroll
;   for (int r = 0; r < 16; ++r) p0[r] = __builtin_amdgcn_exp2f(p0[r]);
; }
; __device__ __forceinline__ void finishSM(f32x16& p0, f32x16& p1, float alpha, float& l_reg, bf16x8& pa0, bf16x8& pa1, bf16x8& pa2, bf16x8& pa3) {
; #pragma unroll
;   for (int r = 0; r < 16; ++r) p1[r] = __builtin_amdgcn_exp2f(p1[r]);
;   float ps = 0;
; #pragma unroll
;   for (int r = 0; r < 16; ++r) ps += p0[r];
; #pragma unroll
;   for (int r = 0; r < 16; ++r) ps += p1[r];
;   { auto rr = __builtin_amdgcn_permlane32_swap(__float_as_uint(ps), __float_as_uint(ps), false, false);
;     ps = __uint_as_float(rr[0]) + __uint_as_float(rr[1]); }
;   l_reg = l_reg * alpha + ps;
;     ...
;   PK4(p0, 0, pa0); PK4(p0, 8, pa1); PK4(p1, 0, pa2); PK4(p1, 8, pa3);
.Lw2slow_g1b:
	v_sub_f32_e32 v227, v227, v188
	v_max_f32_e32 v228, v223, v227
	v_sub_f32_e32 v227, v223, v228
	v_exp_f32_e32 v227, v227
	v_mov_b32_e32 v223, v228
	v_add_f32_e32 v224, v188, v228
	v_sub_f32_e32 v188, 0, v223
	v_mov_b32_e32 v116, v188
	v_mov_b32_e32 v117, v188
	v_mov_b32_e32 v118, v188
	v_mov_b32_e32 v119, v188
	v_mov_b32_e32 v120, v188
	v_mov_b32_e32 v121, v188
	v_mov_b32_e32 v122, v188
	v_mov_b32_e32 v123, v188
	v_mov_b32_e32 v124, v188
	v_mov_b32_e32 v125, v188
	v_mov_b32_e32 v126, v188
	v_mov_b32_e32 v127, v188
	v_mov_b32_e32 v128, v188
	v_mov_b32_e32 v129, v188
	v_mov_b32_e32 v130, v188
	v_mov_b32_e32 v131, v188
	s_and_saveexec_b64 s[72:73], s[38:39]
	ds_write_b32 v213, v227 offset:128
	s_or_b64 exec, exec, s[72:73]
	s_waitcnt lgkmcnt(0)
	v_add_u32_e32 v229, s4, v215
	ds_read_b128 v[230:233], v229 offset:224
	ds_read_b128 v[234:237], v229 offset:192
	ds_read_b128 v[238:241], v229 offset:160
	ds_read_b128 v[242:245], v229 offset:128
	s_waitcnt lgkmcnt(0)
	v_pk_mul_f32 v[44:45], v[44:45], v[230:231]
	v_pk_mul_f32 v[40:41], v[40:41], v[234:235]
	v_pk_mul_f32 v[36:37], v[36:37], v[238:239]
	v_pk_mul_f32 v[46:47], v[46:47], v[232:233]
	v_pk_mul_f32 v[42:43], v[42:43], v[236:237]
	v_pk_mul_f32 v[38:39], v[38:39], v[240:241]
	v_pk_mul_f32 v[34:35], v[34:35], v[244:245]
	v_pk_mul_f32 v[32:33], v[32:33], v[242:243]
	v_pk_mul_f32 v[60:61], v[60:61], v[230:231]
	v_pk_mul_f32 v[56:57], v[56:57], v[234:235]
	v_pk_mul_f32 v[52:53], v[52:53], v[238:239]
	v_pk_mul_f32 v[62:63], v[62:63], v[232:233]
	v_pk_mul_f32 v[58:59], v[58:59], v[236:237]
	v_pk_mul_f32 v[54:55], v[54:55], v[240:241]
	v_pk_mul_f32 v[50:51], v[50:51], v[244:245]
	v_pk_mul_f32 v[48:49], v[48:49], v[242:243]
	v_pk_mul_f32 v[28:29], v[28:29], v[230:231]
	v_pk_mul_f32 v[24:25], v[24:25], v[234:235]
	v_pk_mul_f32 v[20:21], v[20:21], v[238:239]
	v_pk_mul_f32 v[30:31], v[30:31], v[232:233]
	v_pk_mul_f32 v[26:27], v[26:27], v[236:237]
	v_pk_mul_f32 v[22:23], v[22:23], v[240:241]
	v_pk_mul_f32 v[18:19], v[18:19], v[244:245]
	v_pk_mul_f32 v[16:17], v[16:17], v[242:243]
	v_pk_mul_f32 v[12:13], v[12:13], v[230:231]
	v_pk_mul_f32 v[8:9], v[8:9], v[234:235]
	v_pk_mul_f32 v[4:5], v[4:5], v[238:239]
	v_pk_mul_f32 v[14:15], v[14:15], v[232:233]
	v_pk_mul_f32 v[10:11], v[10:11], v[236:237]
	v_pk_mul_f32 v[6:7], v[6:7], v[240:241]
	v_pk_mul_f32 v[2:3], v[2:3], v[244:245]
	v_pk_mul_f32 v[0:1], v[0:1], v[242:243]
	v_mul_f32_e32 v222, v222, v227
	v_sub_f32_e32 v64, v64, v224
	v_exp_f32_e32 v64, v64
	v_sub_f32_e32 v65, v65, v224
	v_exp_f32_e32 v65, v65
	v_sub_f32_e32 v66, v66, v224
	v_exp_f32_e32 v66, v66
	v_add_f32_e32 v246, v65, v64
	v_sub_f32_e32 v67, v67, v224
	v_exp_f32_e32 v67, v67
	v_add_f32_e32 v246, v66, v246
	v_sub_f32_e32 v68, v68, v224
	v_exp_f32_e32 v68, v68
	v_add_f32_e32 v246, v67, v246
	v_sub_f32_e32 v69, v69, v224
	v_exp_f32_e32 v69, v69
	v_add_f32_e32 v246, v68, v246
	v_sub_f32_e32 v70, v70, v224
	v_exp_f32_e32 v70, v70
	v_add_f32_e32 v246, v69, v246
	v_sub_f32_e32 v71, v71, v224
	v_exp_f32_e32 v71, v71
	v_add_f32_e32 v246, v70, v246
	v_sub_f32_e32 v72, v72, v224
	v_exp_f32_e32 v72, v72
	v_add_f32_e32 v246, v71, v246
	v_sub_f32_e32 v73, v73, v224
	v_exp_f32_e32 v73, v73
	v_add_f32_e32 v246, v72, v246
	v_sub_f32_e32 v74, v74, v224
	v_exp_f32_e32 v74, v74
	v_add_f32_e32 v246, v73, v246
	v_sub_f32_e32 v75, v75, v224
	v_exp_f32_e32 v75, v75
	v_add_f32_e32 v246, v74, v246
	v_sub_f32_e32 v76, v76, v224
	v_exp_f32_e32 v228, v76
	v_add_f32_e32 v246, v75, v246
	v_sub_f32_e32 v77, v77, v224
	v_exp_f32_e32 v229, v77
	v_add_f32_e32 v246, v228, v246
	v_sub_f32_e32 v78, v78, v224
	v_exp_f32_e32 v230, v78
	v_add_f32_e32 v246, v229, v246
	v_sub_f32_e32 v79, v79, v224
	v_exp_f32_e32 v231, v79
	v_add_f32_e32 v246, v230, v246
	v_sub_f32_e32 v80, v80, v224
	v_exp_f32_e32 v80, v80
	v_add_f32_e32 v246, v231, v246
	v_sub_f32_e32 v81, v81, v224
	v_exp_f32_e32 v81, v81
	v_add_f32_e32 v246, v80, v246
	v_sub_f32_e32 v82, v82, v224
	v_exp_f32_e32 v82, v82
	v_add_f32_e32 v246, v81, v246
	v_sub_f32_e32 v83, v83, v224
	v_exp_f32_e32 v83, v83
	v_add_f32_e32 v246, v82, v246
	v_sub_f32_e32 v84, v84, v224
	v_exp_f32_e32 v84, v84
	v_add_f32_e32 v246, v83, v246
	v_sub_f32_e32 v85, v85, v224
	v_exp_f32_e32 v85, v85
	v_add_f32_e32 v246, v84, v246
	v_sub_f32_e32 v86, v86, v224
	v_exp_f32_e32 v86, v86
	v_add_f32_e32 v246, v85, v246
	v_sub_f32_e32 v87, v87, v224
	v_exp_f32_e32 v87, v87
	v_add_f32_e32 v246, v86, v246
	v_sub_f32_e32 v88, v88, v224
	v_exp_f32_e32 v88, v88
	v_add_f32_e32 v246, v87, v246
	v_sub_f32_e32 v89, v89, v224
	v_exp_f32_e32 v89, v89
	v_add_f32_e32 v246, v88, v246
	v_sub_f32_e32 v90, v90, v224
	v_exp_f32_e32 v90, v90
	v_add_f32_e32 v246, v89, v246
	v_sub_f32_e32 v91, v91, v224
	v_exp_f32_e32 v91, v91
	v_add_f32_e32 v246, v90, v246
	v_sub_f32_e32 v92, v92, v224
	v_exp_f32_e32 v92, v92
	v_add_f32_e32 v246, v91, v246
	v_sub_f32_e32 v93, v93, v224
	v_exp_f32_e32 v93, v93
	v_add_f32_e32 v246, v92, v246
	v_sub_f32_e32 v94, v94, v224
	v_exp_f32_e32 v94, v94
	v_add_f32_e32 v246, v93, v246
	v_sub_f32_e32 v95, v95, v224
	v_exp_f32_e32 v95, v95
	v_add_f32_e32 v246, v94, v246
	v_cvt_pk_bf16_f32 v76, v64, v65
	v_add_f32_e32 v246, v95, v246
	v_mov_b32_e32 v247, v246
	v_cvt_pk_bf16_f32 v77, v66, v67
	v_cvt_pk_bf16_f32 v78, v68, v69
	v_cvt_pk_bf16_f32 v79, v70, v71
	v_cvt_pk_bf16_f32 v72, v72, v73
	v_cvt_pk_bf16_f32 v73, v74, v75
	v_cvt_pk_bf16_f32 v74, v228, v229
	v_cvt_pk_bf16_f32 v75, v230, v231
	v_cvt_pk_bf16_f32 v68, v80, v81
	v_cvt_pk_bf16_f32 v69, v82, v83
	v_cvt_pk_bf16_f32 v70, v84, v85
	v_cvt_pk_bf16_f32 v71, v86, v87
	v_cvt_pk_bf16_f32 v64, v88, v89
	v_cvt_pk_bf16_f32 v65, v90, v91
	v_cvt_pk_bf16_f32 v66, v92, v93
	v_cvt_pk_bf16_f32 v67, v94, v95
	v_permlane32_swap_b32_e32 v246, v247
	v_add_f32_e32 v222, v222, v246
	v_add_f32_e32 v222, v222, v247
	s_branch .Lw2join_g1b
; __device__ __forceinline__ void partialSM(f32x16& p0, f32x16& p1, float& m_reg, float& alpha) {
;     ...
;   if (__builtin_expect(__all(pmax - m_reg <= THR2), 1)) { mn = m_reg; alpha = 1.f; }
;   else { mn = fmaxf(m_reg, pmax); alpha = __builtin_amdgcn_exp2f(m_reg - mn); m_reg = mn; }
; #pragma unroll
;   for (int r = 0; r < 16; ++r) { p0[r] -= mn; p1[r] -= mn; }
; #pragma unroll
;   for (int r = 0; r < 16; ++r) p0[r] = __builtin_amdgcn_exp2f(p0[r]);
; }
; __device__ __forceinline__ void finishSM(f32x16& p0, f32x16& p1, float alpha, float& l_reg, bf16x8& pa0, bf16x8& pa1, bf16x8& pa2, bf16x8& pa3) {
; #pragma unroll
;   for (int r = 0; r < 16; ++r) p1[r] = __builtin_amdgcn_exp2f(p1[r]);
;   float ps = 0;
; #pragma unroll
;   for (int r = 0; r < 16; ++r) ps += p0[r];
; #pragma unroll
;   for (int r = 0; r < 16; ++r) ps += p1[r];
;   { auto rr = __builtin_amdgcn_permlane32_swap(__float_as_uint(ps), __float_as_uint(ps), false, false);
;     ps = __uint_as_float(rr[0]) + __uint_as_float(rr[1]); }
;   l_reg = l_reg * alpha + ps;
;     ...
;   PK4(p0, 0, pa0); PK4(p0, 8, pa1); PK4(p1, 0, pa2); PK4(p1, 8, pa3);
.Lw2slow_g0a:
	v_sub_f32_e32 v161, v161, v232
	v_max_f32_e32 v163, v162, v161
	v_sub_f32_e32 v161, v162, v163
	v_exp_f32_e32 v161, v161
	v_mov_b32_e32 v162, v163
	v_add_f32_e32 v163, v232, v163
	v_sub_f32_e32 v232, 0, v162
	v_mov_b32_e32 v216, v232
	v_mov_b32_e32 v217, v232
	v_mov_b32_e32 v218, v232
	v_mov_b32_e32 v219, v232
	v_mov_b32_e32 v220, v232
	v_mov_b32_e32 v221, v232
	v_mov_b32_e32 v222, v232
	v_mov_b32_e32 v223, v232
	v_mov_b32_e32 v224, v232
	v_mov_b32_e32 v225, v232
	v_mov_b32_e32 v226, v232
	v_mov_b32_e32 v227, v232
	v_mov_b32_e32 v228, v232
	v_mov_b32_e32 v229, v232
	v_mov_b32_e32 v230, v232
	v_mov_b32_e32 v231, v232
	v_mov_b32_e32 v233, s19
	s_and_saveexec_b64 s[72:73], s[38:39]
	ds_write_b32 v213, v161 offset:128
	s_or_b64 exec, exec, s[72:73]
	s_waitcnt lgkmcnt(0)
	v_add_u32_e32 v194, s4, v215
	ds_read_b128 v[164:167], v194 offset:224
	ds_read_b128 v[168:171], v194 offset:192
	ds_read_b128 v[172:175], v194 offset:160
	ds_read_b128 v[176:179], v194 offset:128
	s_waitcnt lgkmcnt(0)
	v_pk_mul_f32 v[44:45], v[44:45], v[164:165]
	v_pk_mul_f32 v[40:41], v[40:41], v[168:169]
	v_pk_mul_f32 v[36:37], v[36:37], v[172:173]
	v_pk_mul_f32 v[46:47], v[46:47], v[166:167]
	v_pk_mul_f32 v[42:43], v[42:43], v[170:171]
	v_pk_mul_f32 v[38:39], v[38:39], v[174:175]
	v_pk_mul_f32 v[34:35], v[34:35], v[178:179]
	v_pk_mul_f32 v[32:33], v[32:33], v[176:177]
	v_pk_mul_f32 v[60:61], v[60:61], v[164:165]
	v_pk_mul_f32 v[56:57], v[56:57], v[168:169]
	v_pk_mul_f32 v[52:53], v[52:53], v[172:173]
	v_pk_mul_f32 v[62:63], v[62:63], v[166:167]
	v_pk_mul_f32 v[58:59], v[58:59], v[170:171]
	v_pk_mul_f32 v[54:55], v[54:55], v[174:175]
	v_pk_mul_f32 v[50:51], v[50:51], v[178:179]
	v_pk_mul_f32 v[48:49], v[48:49], v[176:177]
	v_pk_mul_f32 v[28:29], v[28:29], v[164:165]
	v_pk_mul_f32 v[24:25], v[24:25], v[168:169]
	v_pk_mul_f32 v[20:21], v[20:21], v[172:173]
	v_pk_mul_f32 v[30:31], v[30:31], v[166:167]
	v_pk_mul_f32 v[26:27], v[26:27], v[170:171]
	v_pk_mul_f32 v[22:23], v[22:23], v[174:175]
	v_pk_mul_f32 v[18:19], v[18:19], v[178:179]
	v_pk_mul_f32 v[16:17], v[16:17], v[176:177]
	v_pk_mul_f32 v[12:13], v[12:13], v[164:165]
	v_pk_mul_f32 v[8:9], v[8:9], v[168:169]
	v_pk_mul_f32 v[4:5], v[4:5], v[172:173]
	v_pk_mul_f32 v[14:15], v[14:15], v[166:167]
	v_pk_mul_f32 v[10:11], v[10:11], v[170:171]
	v_pk_mul_f32 v[6:7], v[6:7], v[174:175]
	v_pk_mul_f32 v[2:3], v[2:3], v[178:179]
	v_pk_mul_f32 v[0:1], v[0:1], v[176:177]
	v_mul_f32_e32 v156, v156, v161
	v_sub_f32_e32 v64, v64, v163
	v_exp_f32_e32 v64, v64
	v_sub_f32_e32 v65, v65, v163
	v_exp_f32_e32 v65, v65
	v_sub_f32_e32 v66, v66, v163
	v_exp_f32_e32 v66, v66
	v_add_f32_e32 v188, v65, v64
	v_sub_f32_e32 v67, v67, v163
	v_exp_f32_e32 v67, v67
	v_add_f32_e32 v188, v66, v188
	v_sub_f32_e32 v68, v68, v163
	v_exp_f32_e32 v68, v68
	v_add_f32_e32 v188, v67, v188
	v_sub_f32_e32 v69, v69, v163
	v_exp_f32_e32 v69, v69
	v_add_f32_e32 v188, v68, v188
	v_sub_f32_e32 v70, v70, v163
	v_exp_f32_e32 v70, v70
	v_add_f32_e32 v188, v69, v188
	v_sub_f32_e32 v71, v71, v163
	v_exp_f32_e32 v71, v71
	v_add_f32_e32 v188, v70, v188
	v_sub_f32_e32 v72, v72, v163
	v_exp_f32_e32 v72, v72
	v_add_f32_e32 v188, v71, v188
	v_sub_f32_e32 v73, v73, v163
	v_exp_f32_e32 v73, v73
	v_add_f32_e32 v188, v72, v188
	v_sub_f32_e32 v74, v74, v163
	v_exp_f32_e32 v74, v74
	v_add_f32_e32 v188, v73, v188
	v_sub_f32_e32 v75, v75, v163
	v_exp_f32_e32 v75, v75
	v_add_f32_e32 v188, v74, v188
	v_sub_f32_e32 v76, v76, v163
	v_exp_f32_e32 v76, v76
	v_add_f32_e32 v188, v75, v188
	v_sub_f32_e32 v77, v77, v163
	v_exp_f32_e32 v77, v77
	v_add_f32_e32 v188, v76, v188
	v_sub_f32_e32 v78, v78, v163
	v_exp_f32_e32 v78, v78
	v_add_f32_e32 v188, v77, v188
	v_sub_f32_e32 v79, v79, v163
	v_exp_f32_e32 v79, v79
	v_add_f32_e32 v188, v78, v188
	v_sub_f32_e32 v80, v80, v163
	v_exp_f32_e32 v80, v80
	v_add_f32_e32 v188, v79, v188
	v_sub_f32_e32 v81, v81, v163
	v_exp_f32_e32 v81, v81
	v_add_f32_e32 v188, v80, v188
	v_sub_f32_e32 v82, v82, v163
	v_exp_f32_e32 v82, v82
	v_add_f32_e32 v188, v81, v188
	v_sub_f32_e32 v83, v83, v163
	v_exp_f32_e32 v83, v83
	v_add_f32_e32 v188, v82, v188
	v_sub_f32_e32 v84, v84, v163
	v_exp_f32_e32 v84, v84
	v_add_f32_e32 v188, v83, v188
	v_sub_f32_e32 v85, v85, v163
	v_exp_f32_e32 v85, v85
	v_add_f32_e32 v188, v84, v188
	v_sub_f32_e32 v86, v86, v163
	v_exp_f32_e32 v86, v86
	v_add_f32_e32 v188, v85, v188
	v_sub_f32_e32 v87, v87, v163
	v_exp_f32_e32 v87, v87
	v_add_f32_e32 v188, v86, v188
	v_sub_f32_e32 v88, v88, v163
	v_exp_f32_e32 v88, v88
	v_add_f32_e32 v188, v87, v188
	v_sub_f32_e32 v89, v89, v163
	v_exp_f32_e32 v89, v89
	v_add_f32_e32 v188, v88, v188
	v_sub_f32_e32 v90, v90, v163
	v_exp_f32_e32 v90, v90
	v_add_f32_e32 v188, v89, v188
	v_sub_f32_e32 v91, v91, v163
	v_exp_f32_e32 v91, v91
	v_add_f32_e32 v188, v90, v188
	v_sub_f32_e32 v92, v92, v163
	v_exp_f32_e32 v92, v92
	v_add_f32_e32 v188, v91, v188
	v_sub_f32_e32 v93, v93, v163
	v_exp_f32_e32 v93, v93
	v_add_f32_e32 v188, v92, v188
	v_sub_f32_e32 v94, v94, v163
	v_exp_f32_e32 v94, v94
	v_add_f32_e32 v188, v93, v188
	v_sub_f32_e32 v95, v95, v163
	v_exp_f32_e32 v95, v95
	v_add_f32_e32 v188, v94, v188
	v_cvt_pk_bf16_f32 v64, v64, v65
	v_add_f32_e32 v188, v95, v188
	v_mov_b32_e32 v189, v188
	v_cvt_pk_bf16_f32 v65, v66, v67
	v_cvt_pk_bf16_f32 v66, v68, v69
	v_cvt_pk_bf16_f32 v67, v70, v71
	v_cvt_pk_bf16_f32 v68, v72, v73
	v_cvt_pk_bf16_f32 v69, v74, v75
	v_cvt_pk_bf16_f32 v70, v76, v77
	v_cvt_pk_bf16_f32 v71, v78, v79
	v_cvt_pk_bf16_f32 v72, v80, v81
	v_cvt_pk_bf16_f32 v73, v82, v83
	v_cvt_pk_bf16_f32 v74, v84, v85
	v_cvt_pk_bf16_f32 v75, v86, v87
	v_cvt_pk_bf16_f32 v76, v88, v89
	v_cvt_pk_bf16_f32 v77, v90, v91
	v_cvt_pk_bf16_f32 v78, v92, v93
	v_cvt_pk_bf16_f32 v79, v94, v95
	v_permlane32_swap_b32_e32 v188, v189
	v_add_f32_e32 v156, v156, v188
	v_add_f32_e32 v156, v156, v189
	s_branch .Lw2join_g0a
; __device__ __forceinline__ void partialSM(f32x16& p0, f32x16& p1, float& m_reg, float& alpha) {
;     ...
;   if (__builtin_expect(__all(pmax - m_reg <= THR2), 1)) { mn = m_reg; alpha = 1.f; }
;   else { mn = fmaxf(m_reg, pmax); alpha = __builtin_amdgcn_exp2f(m_reg - mn); m_reg = mn; }
; #pragma unroll
;   for (int r = 0; r < 16; ++r) { p0[r] -= mn; p1[r] -= mn; }
; #pragma unroll
;   for (int r = 0; r < 16; ++r) p0[r] = __builtin_amdgcn_exp2f(p0[r]);
; }
; __device__ __forceinline__ void finishSM(f32x16& p0, f32x16& p1, float alpha, float& l_reg, bf16x8& pa0, bf16x8& pa1, bf16x8& pa2, bf16x8& pa3) {
; #pragma unroll
;   for (int r = 0; r < 16; ++r) p1[r] = __builtin_amdgcn_exp2f(p1[r]);
;   float ps = 0;
; #pragma unroll
;   for (int r = 0; r < 16; ++r) ps += p0[r];
; #pragma unroll
;   for (int r = 0; r < 16; ++r) ps += p1[r];
;   { auto rr = __builtin_amdgcn_permlane32_swap(__float_as_uint(ps), __float_as_uint(ps), false, false);
;     ps = __uint_as_float(rr[0]) + __uint_as_float(rr[1]); }
;   l_reg = l_reg * alpha + ps;
;     ...
;   PK4(p0, 0, pa0); PK4(p0, 8, pa1); PK4(p1, 0, pa2); PK4(p1, 8, pa3);
.Lw2slow_g0b:
	v_sub_f32_e32 v152, v152, v232
	v_max_f32_e32 v153, v162, v152
	v_sub_f32_e32 v152, v162, v153
	v_exp_f32_e32 v152, v152
	v_mov_b32_e32 v162, v153
	v_add_f32_e32 v163, v232, v153
	v_sub_f32_e32 v232, 0, v162
	v_mov_b32_e32 v216, v232
	v_mov_b32_e32 v217, v232
	v_mov_b32_e32 v218, v232
	v_mov_b32_e32 v219, v232
	v_mov_b32_e32 v220, v232
	v_mov_b32_e32 v221, v232
	v_mov_b32_e32 v222, v232
	v_mov_b32_e32 v223, v232
	v_mov_b32_e32 v224, v232
	v_mov_b32_e32 v225, v232
	v_mov_b32_e32 v226, v232
	v_mov_b32_e32 v227, v232
	v_mov_b32_e32 v228, v232
	v_mov_b32_e32 v229, v232
	v_mov_b32_e32 v230, v232
	v_mov_b32_e32 v231, v232
	v_mov_b32_e32 v233, s19
	s_and_saveexec_b64 s[72:73], s[38:39]
	ds_write_b32 v213, v152 offset:128
	s_or_b64 exec, exec, s[72:73]
	s_waitcnt lgkmcnt(0)
	v_add_u32_e32 v154, s4, v215
	ds_read_b128 v[166:169], v154 offset:224
	ds_read_b128 v[170:173], v154 offset:192
	ds_read_b128 v[174:177], v154 offset:160
	ds_read_b128 v[188:191], v154 offset:128
	s_waitcnt lgkmcnt(0)
	v_pk_mul_f32 v[44:45], v[44:45], v[166:167]
	v_pk_mul_f32 v[40:41], v[40:41], v[170:171]
	v_pk_mul_f32 v[36:37], v[36:37], v[174:175]
	v_pk_mul_f32 v[46:47], v[46:47], v[168:169]
	v_pk_mul_f32 v[42:43], v[42:43], v[172:173]
	v_pk_mul_f32 v[38:39], v[38:39], v[176:177]
	v_pk_mul_f32 v[34:35], v[34:35], v[190:191]
	v_pk_mul_f32 v[32:33], v[32:33], v[188:189]
	v_pk_mul_f32 v[60:61], v[60:61], v[166:167]
	v_pk_mul_f32 v[56:57], v[56:57], v[170:171]
	v_pk_mul_f32 v[52:53], v[52:53], v[174:175]
	v_pk_mul_f32 v[62:63], v[62:63], v[168:169]
	v_pk_mul_f32 v[58:59], v[58:59], v[172:173]
	v_pk_mul_f32 v[54:55], v[54:55], v[176:177]
	v_pk_mul_f32 v[50:51], v[50:51], v[190:191]
	v_pk_mul_f32 v[48:49], v[48:49], v[188:189]
	v_pk_mul_f32 v[28:29], v[28:29], v[166:167]
	v_pk_mul_f32 v[24:25], v[24:25], v[170:171]
	v_pk_mul_f32 v[20:21], v[20:21], v[174:175]
	v_pk_mul_f32 v[30:31], v[30:31], v[168:169]
	v_pk_mul_f32 v[26:27], v[26:27], v[172:173]
	v_pk_mul_f32 v[22:23], v[22:23], v[176:177]
	v_pk_mul_f32 v[18:19], v[18:19], v[190:191]
	v_pk_mul_f32 v[16:17], v[16:17], v[188:189]
	v_pk_mul_f32 v[12:13], v[12:13], v[166:167]
	v_pk_mul_f32 v[8:9], v[8:9], v[170:171]
	v_pk_mul_f32 v[4:5], v[4:5], v[174:175]
	v_pk_mul_f32 v[14:15], v[14:15], v[168:169]
	v_pk_mul_f32 v[10:11], v[10:11], v[172:173]
	v_pk_mul_f32 v[6:7], v[6:7], v[176:177]
	v_pk_mul_f32 v[2:3], v[2:3], v[190:191]
	v_pk_mul_f32 v[0:1], v[0:1], v[188:189]
	v_mul_f32_e32 v156, v156, v152
	v_sub_f32_e32 v64, v64, v163
	v_exp_f32_e32 v64, v64
	v_sub_f32_e32 v65, v65, v163
	v_exp_f32_e32 v65, v65
	v_sub_f32_e32 v66, v66, v163
	v_exp_f32_e32 v66, v66
	v_add_f32_e32 v190, v65, v64
	v_sub_f32_e32 v67, v67, v163
	v_exp_f32_e32 v67, v67
	v_add_f32_e32 v190, v66, v190
	v_sub_f32_e32 v68, v68, v163
	v_exp_f32_e32 v68, v68
	v_add_f32_e32 v190, v67, v190
	v_sub_f32_e32 v69, v69, v163
	v_exp_f32_e32 v69, v69
	v_add_f32_e32 v190, v68, v190
	v_sub_f32_e32 v70, v70, v163
	v_exp_f32_e32 v70, v70
	v_add_f32_e32 v190, v69, v190
	v_sub_f32_e32 v71, v71, v163
	v_exp_f32_e32 v71, v71
	v_add_f32_e32 v190, v70, v190
	v_sub_f32_e32 v72, v72, v163
	v_exp_f32_e32 v72, v72
	v_add_f32_e32 v190, v71, v190
	v_sub_f32_e32 v73, v73, v163
	v_exp_f32_e32 v73, v73
	v_add_f32_e32 v190, v72, v190
	v_sub_f32_e32 v74, v74, v163
	v_exp_f32_e32 v74, v74
	v_add_f32_e32 v190, v73, v190
	v_sub_f32_e32 v75, v75, v163
	v_exp_f32_e32 v75, v75
	v_add_f32_e32 v190, v74, v190
	v_sub_f32_e32 v76, v76, v163
	v_exp_f32_e32 v153, v76
	v_add_f32_e32 v190, v75, v190
	v_sub_f32_e32 v77, v77, v163
	v_exp_f32_e32 v154, v77
	v_add_f32_e32 v190, v153, v190
	v_sub_f32_e32 v78, v78, v163
	v_exp_f32_e32 v155, v78
	v_add_f32_e32 v190, v154, v190
	v_sub_f32_e32 v79, v79, v163
	v_exp_f32_e32 v165, v79
	v_add_f32_e32 v190, v155, v190
	v_sub_f32_e32 v80, v80, v163
	v_exp_f32_e32 v80, v80
	v_add_f32_e32 v190, v165, v190
	v_sub_f32_e32 v81, v81, v163
	v_exp_f32_e32 v81, v81
	v_add_f32_e32 v190, v80, v190
	v_sub_f32_e32 v82, v82, v163
	v_exp_f32_e32 v82, v82
	v_add_f32_e32 v190, v81, v190
	v_sub_f32_e32 v83, v83, v163
	v_exp_f32_e32 v83, v83
	v_add_f32_e32 v190, v82, v190
	v_sub_f32_e32 v84, v84, v163
	v_exp_f32_e32 v84, v84
	v_add_f32_e32 v190, v83, v190
	v_sub_f32_e32 v85, v85, v163
	v_exp_f32_e32 v85, v85
	v_add_f32_e32 v190, v84, v190
	v_sub_f32_e32 v86, v86, v163
	v_exp_f32_e32 v86, v86
	v_add_f32_e32 v190, v85, v190
	v_sub_f32_e32 v87, v87, v163
	v_exp_f32_e32 v87, v87
	v_add_f32_e32 v190, v86, v190
	v_sub_f32_e32 v88, v88, v163
	v_exp_f32_e32 v88, v88
	v_add_f32_e32 v190, v87, v190
	v_sub_f32_e32 v89, v89, v163
	v_exp_f32_e32 v89, v89
	v_add_f32_e32 v190, v88, v190
	v_sub_f32_e32 v90, v90, v163
	v_exp_f32_e32 v90, v90
	v_add_f32_e32 v190, v89, v190
	v_sub_f32_e32 v91, v91, v163
	v_exp_f32_e32 v91, v91
	v_add_f32_e32 v190, v90, v190
	v_sub_f32_e32 v92, v92, v163
	v_exp_f32_e32 v92, v92
	v_add_f32_e32 v190, v91, v190
	v_sub_f32_e32 v93, v93, v163
	v_exp_f32_e32 v93, v93
	v_add_f32_e32 v190, v92, v190
	v_sub_f32_e32 v94, v94, v163
	v_exp_f32_e32 v94, v94
	v_add_f32_e32 v190, v93, v190
	v_sub_f32_e32 v95, v95, v163
	v_exp_f32_e32 v95, v95
	v_add_f32_e32 v190, v94, v190
	v_cvt_pk_bf16_f32 v76, v64, v65
	v_add_f32_e32 v190, v95, v190
	v_mov_b32_e32 v191, v190
	v_cvt_pk_bf16_f32 v77, v66, v67
	v_cvt_pk_bf16_f32 v78, v68, v69
	v_cvt_pk_bf16_f32 v79, v70, v71
	v_cvt_pk_bf16_f32 v72, v72, v73
	v_cvt_pk_bf16_f32 v73, v74, v75
	v_cvt_pk_bf16_f32 v74, v153, v154
	v_cvt_pk_bf16_f32 v75, v155, v165
	v_cvt_pk_bf16_f32 v68, v80, v81
	v_cvt_pk_bf16_f32 v69, v82, v83
	v_cvt_pk_bf16_f32 v70, v84, v85
	v_cvt_pk_bf16_f32 v71, v86, v87
	v_cvt_pk_bf16_f32 v64, v88, v89
	v_cvt_pk_bf16_f32 v65, v90, v91
	v_cvt_pk_bf16_f32 v66, v92, v93
	v_cvt_pk_bf16_f32 v67, v94, v95
	v_permlane32_swap_b32_e32 v190, v191
	v_add_f32_e32 v156, v156, v190
	v_add_f32_e32 v156, v156, v191
	s_branch .Lw2join_g0b
